# MFMA order within each phase: activation-fragment operand (srcB) held for 4 consecutive MFMAs (snake), on top of combo4
# speedup vs baseline: 1.0025x; 1.0005x over previous
.LBB0_175:
	s_add_i32 s29, s29, 2
	s_mov_b32 s44, s29
	s_ashr_i32 s45, s44, 31
	s_lshl_b64 s[82:83], s[44:45], 7
	s_add_u32 s45, s82, 0x100
	s_addc_u32 s81, s83, 0
	s_add_u32 s84, s42, s45
	s_addc_u32 s85, s43, s81
	s_add_u32 s86, s40, s45
	s_addc_u32 s81, s41, s81
	s_cmp_eq_u32 s44, 14
	s_cselect_b32 s45, s75, s85
	s_cselect_b32 s44, s76, s84
	s_cselect_b32 s85, s31, s81
	s_cselect_b32 s84, s74, s86
	s_add_u32 s82, s42, s82
	s_addc_u32 s83, s43, s83
	v_lshl_add_u64 v[212:213], s[82:83], 0, v[130:131]
	s_mov_b32 m0, s66
	v_lshl_add_u64 v[214:215], v[212:213], 0, s[22:23]
	global_load_lds_dwordx4 v[214:215], off
	v_lshl_add_u64 v[212:213], v[212:213], 0, s[24:25]
	s_mov_b32 m0, s67
	s_nop 0
	global_load_lds_dwordx4 v[212:213], off
	ds_read_b128 v[146:149], v141
	ds_read_b128 v[150:153], v141 offset:1024
	ds_read_b128 v[154:157], v141 offset:2048
	ds_read_b128 v[158:161], v141 offset:3072
	ds_read_b128 v[162:165], v142
	ds_read_b128 v[166:169], v142 offset:1024
	ds_read_b128 v[170:173], v142 offset:2048
	ds_read_b128 v[174:177], v142 offset:3072
	ds_read_b128 v[178:181], v143
	ds_read_b128 v[182:185], v143 offset:1024
	ds_read_b128 v[186:189], v143 offset:2048
	ds_read_b128 v[190:193], v143 offset:3072
	ds_read_b128 v[194:197], v143 offset:4096
	ds_read_b128 v[198:201], v143 offset:5120
	ds_read_b128 v[202:205], v143 offset:6144
	ds_read_b128 v[206:209], v143 offset:7168
	s_waitcnt vmcnt(8)
	s_waitcnt lgkmcnt(0)
	s_barrier
	s_waitcnt lgkmcnt(0)
	v_mfma_f32_16x16x32_bf16 v[124:127], v[146:149], v[178:181], v[124:127]
	v_mfma_f32_16x16x32_bf16 v[112:115], v[154:157], v[178:181], v[112:115]
	v_mfma_f32_16x16x32_bf16 v[120:123], v[162:165], v[178:181], v[120:123]
	v_mfma_f32_16x16x32_bf16 v[116:119], v[170:173], v[178:181], v[116:119]
	v_mfma_f32_16x16x32_bf16 v[100:103], v[170:173], v[186:189], v[100:103]
	v_mfma_f32_16x16x32_bf16 v[104:107], v[162:165], v[186:189], v[104:107]
	v_mfma_f32_16x16x32_bf16 v[96:99], v[154:157], v[186:189], v[96:99]
	v_mfma_f32_16x16x32_bf16 v[108:111], v[146:149], v[186:189], v[108:111]
	v_mfma_f32_16x16x32_bf16 v[92:95], v[146:149], v[194:197], v[92:95]
	v_mfma_f32_16x16x32_bf16 v[80:83], v[154:157], v[194:197], v[80:83]
	v_mfma_f32_16x16x32_bf16 v[88:91], v[162:165], v[194:197], v[88:91]
	v_mfma_f32_16x16x32_bf16 v[84:87], v[170:173], v[194:197], v[84:87]
	v_mfma_f32_16x16x32_bf16 v[68:71], v[170:173], v[202:205], v[68:71]
	v_mfma_f32_16x16x32_bf16 v[72:75], v[162:165], v[202:205], v[72:75]
	v_mfma_f32_16x16x32_bf16 v[64:67], v[154:157], v[202:205], v[64:67]
	v_mfma_f32_16x16x32_bf16 v[76:79], v[146:149], v[202:205], v[76:79]
	v_mfma_f32_16x16x32_bf16 v[124:127], v[150:153], v[182:185], v[124:127]
	v_mfma_f32_16x16x32_bf16 v[112:115], v[158:161], v[182:185], v[112:115]
	v_mfma_f32_16x16x32_bf16 v[120:123], v[166:169], v[182:185], v[120:123]
	v_mfma_f32_16x16x32_bf16 v[116:119], v[174:177], v[182:185], v[116:119]
	v_mfma_f32_16x16x32_bf16 v[100:103], v[174:177], v[190:193], v[100:103]
	v_mfma_f32_16x16x32_bf16 v[104:107], v[166:169], v[190:193], v[104:107]
	v_mfma_f32_16x16x32_bf16 v[96:99], v[158:161], v[190:193], v[96:99]
	v_mfma_f32_16x16x32_bf16 v[108:111], v[150:153], v[190:193], v[108:111]
	v_mfma_f32_16x16x32_bf16 v[92:95], v[150:153], v[198:201], v[92:95]
	v_mfma_f32_16x16x32_bf16 v[80:83], v[158:161], v[198:201], v[80:83]
	v_mfma_f32_16x16x32_bf16 v[88:91], v[166:169], v[198:201], v[88:91]
	v_mfma_f32_16x16x32_bf16 v[84:87], v[174:177], v[198:201], v[84:87]
	v_mfma_f32_16x16x32_bf16 v[68:71], v[174:177], v[206:209], v[68:71]
	v_mfma_f32_16x16x32_bf16 v[72:75], v[166:169], v[206:209], v[72:75]
	v_mfma_f32_16x16x32_bf16 v[64:67], v[158:161], v[206:209], v[64:67]
	v_mfma_f32_16x16x32_bf16 v[76:79], v[150:153], v[206:209], v[76:79]
	s_barrier
	s_mov_b32 m0, s68
	v_lshl_add_u64 v[212:213], s[84:85], 0, v[128:129]
	global_load_lds_dwordx4 v[212:213], off
	v_lshl_add_u64 v[214:215], v[212:213], 0, s[0:1]
	s_mov_b32 m0, s69
	s_nop 0
	global_load_lds_dwordx4 v[214:215], off
	v_lshl_add_u64 v[214:215], v[212:213], 0, s[2:3]
	s_mov_b32 m0, s70
	s_nop 0
	global_load_lds_dwordx4 v[214:215], off
	v_lshl_add_u64 v[214:215], v[212:213], 0, s[8:9]
	s_mov_b32 m0, s71
	s_nop 0
	global_load_lds_dwordx4 v[214:215], off
	v_lshl_add_u64 v[214:215], s[44:45], 0, v[130:131]
	s_mov_b32 m0, s39
	v_lshl_add_u64 v[216:217], v[214:215], 0, s[0:1]
	global_load_lds_dwordx4 v[214:215], off
	s_mov_b32 m0, s56
	s_nop 0
	global_load_lds_dwordx4 v[216:217], off
	ds_read_b128 v[178:181], v143 offset:16384
	ds_read_b128 v[182:185], v143 offset:17408
	ds_read_b128 v[186:189], v143 offset:18432
	ds_read_b128 v[190:193], v143 offset:19456
	ds_read_b128 v[194:197], v143 offset:20480
	ds_read_b128 v[198:201], v143 offset:21504
	ds_read_b128 v[202:205], v143 offset:22528
	ds_read_b128 v[206:209], v143 offset:23552
	s_waitcnt vmcnt(8)
	s_waitcnt lgkmcnt(0)
	s_barrier
	s_waitcnt lgkmcnt(0)
	v_mfma_f32_16x16x32_bf16 v[60:63], v[146:149], v[178:181], v[60:63]
	v_mfma_f32_16x16x32_bf16 v[48:51], v[154:157], v[178:181], v[48:51]
	v_mfma_f32_16x16x32_bf16 v[56:59], v[162:165], v[178:181], v[56:59]
	v_mfma_f32_16x16x32_bf16 v[52:55], v[170:173], v[178:181], v[52:55]
	v_mfma_f32_16x16x32_bf16 v[36:39], v[170:173], v[186:189], v[36:39]
	v_mfma_f32_16x16x32_bf16 v[40:43], v[162:165], v[186:189], v[40:43]
	v_mfma_f32_16x16x32_bf16 v[32:35], v[154:157], v[186:189], v[32:35]
	v_mfma_f32_16x16x32_bf16 v[44:47], v[146:149], v[186:189], v[44:47]
	v_mfma_f32_16x16x32_bf16 v[28:31], v[146:149], v[194:197], v[28:31]
	v_mfma_f32_16x16x32_bf16 v[16:19], v[154:157], v[194:197], v[16:19]
	v_mfma_f32_16x16x32_bf16 v[24:27], v[162:165], v[194:197], v[24:27]
	v_mfma_f32_16x16x32_bf16 v[20:23], v[170:173], v[194:197], v[20:23]
	v_mfma_f32_16x16x32_bf16 v[4:7], v[170:173], v[202:205], v[4:7]
	v_mfma_f32_16x16x32_bf16 v[8:11], v[162:165], v[202:205], v[8:11]
	v_mfma_f32_16x16x32_bf16 v[0:3], v[154:157], v[202:205], v[0:3]
	v_mfma_f32_16x16x32_bf16 v[12:15], v[146:149], v[202:205], v[12:15]
	v_mfma_f32_16x16x32_bf16 v[60:63], v[150:153], v[182:185], v[60:63]
	v_mfma_f32_16x16x32_bf16 v[48:51], v[158:161], v[182:185], v[48:51]
	v_mfma_f32_16x16x32_bf16 v[56:59], v[166:169], v[182:185], v[56:59]
	v_mfma_f32_16x16x32_bf16 v[52:55], v[174:177], v[182:185], v[52:55]
	v_mfma_f32_16x16x32_bf16 v[36:39], v[174:177], v[190:193], v[36:39]
	v_mfma_f32_16x16x32_bf16 v[40:43], v[166:169], v[190:193], v[40:43]
	v_mfma_f32_16x16x32_bf16 v[32:35], v[158:161], v[190:193], v[32:35]
	v_mfma_f32_16x16x32_bf16 v[44:47], v[150:153], v[190:193], v[44:47]
	v_mfma_f32_16x16x32_bf16 v[28:31], v[150:153], v[198:201], v[28:31]
	v_mfma_f32_16x16x32_bf16 v[16:19], v[158:161], v[198:201], v[16:19]
	v_mfma_f32_16x16x32_bf16 v[24:27], v[166:169], v[198:201], v[24:27]
	v_mfma_f32_16x16x32_bf16 v[20:23], v[174:177], v[198:201], v[20:23]
	v_mfma_f32_16x16x32_bf16 v[4:7], v[174:177], v[206:209], v[4:7]
	v_mfma_f32_16x16x32_bf16 v[8:11], v[166:169], v[206:209], v[8:11]
	v_mfma_f32_16x16x32_bf16 v[0:3], v[158:161], v[206:209], v[0:3]
	v_mfma_f32_16x16x32_bf16 v[12:15], v[150:153], v[206:209], v[12:15]
	s_barrier
	s_mov_b32 m0, s57
	v_lshl_add_u64 v[216:217], v[214:215], 0, s[2:3]
	global_load_lds_dwordx4 v[216:217], off
	v_lshl_add_u64 v[216:217], v[214:215], 0, s[8:9]
	s_mov_b32 m0, s58
	s_nop 0
	global_load_lds_dwordx4 v[216:217], off
	ds_read_b128 v[146:149], v144
	ds_read_b128 v[150:153], v144 offset:1024
	ds_read_b128 v[154:157], v144 offset:2048
	ds_read_b128 v[158:161], v144 offset:3072
	ds_read_b128 v[162:165], v136
	ds_read_b128 v[166:169], v136 offset:1024
	ds_read_b128 v[170:173], v136 offset:2048
	ds_read_b128 v[174:177], v136 offset:3072
	ds_read_b128 v[178:181], v143 offset:32768
	ds_read_b128 v[182:185], v143 offset:33792
	ds_read_b128 v[186:189], v143 offset:34816
	ds_read_b128 v[190:193], v143 offset:35840
	ds_read_b128 v[194:197], v143 offset:36864
	ds_read_b128 v[198:201], v143 offset:37888
	ds_read_b128 v[202:205], v143 offset:38912
	ds_read_b128 v[206:209], v143 offset:39936
	s_waitcnt vmcnt(8)
	s_waitcnt lgkmcnt(0)
	s_barrier
	s_waitcnt lgkmcnt(0)
	v_mfma_f32_16x16x32_bf16 v[124:127], v[146:149], v[178:181], v[124:127]
	v_mfma_f32_16x16x32_bf16 v[112:115], v[154:157], v[178:181], v[112:115]
	v_mfma_f32_16x16x32_bf16 v[120:123], v[162:165], v[178:181], v[120:123]
	v_mfma_f32_16x16x32_bf16 v[116:119], v[170:173], v[178:181], v[116:119]
	v_mfma_f32_16x16x32_bf16 v[100:103], v[170:173], v[186:189], v[100:103]
	v_mfma_f32_16x16x32_bf16 v[104:107], v[162:165], v[186:189], v[104:107]
	v_mfma_f32_16x16x32_bf16 v[96:99], v[154:157], v[186:189], v[96:99]
	v_mfma_f32_16x16x32_bf16 v[108:111], v[146:149], v[186:189], v[108:111]
	v_mfma_f32_16x16x32_bf16 v[92:95], v[146:149], v[194:197], v[92:95]
	v_mfma_f32_16x16x32_bf16 v[80:83], v[154:157], v[194:197], v[80:83]
	v_mfma_f32_16x16x32_bf16 v[88:91], v[162:165], v[194:197], v[88:91]
	v_mfma_f32_16x16x32_bf16 v[84:87], v[170:173], v[194:197], v[84:87]
	v_mfma_f32_16x16x32_bf16 v[68:71], v[170:173], v[202:205], v[68:71]
	v_mfma_f32_16x16x32_bf16 v[72:75], v[162:165], v[202:205], v[72:75]
	v_mfma_f32_16x16x32_bf16 v[64:67], v[154:157], v[202:205], v[64:67]
	v_mfma_f32_16x16x32_bf16 v[76:79], v[146:149], v[202:205], v[76:79]
	v_mfma_f32_16x16x32_bf16 v[124:127], v[150:153], v[182:185], v[124:127]
	v_mfma_f32_16x16x32_bf16 v[112:115], v[158:161], v[182:185], v[112:115]
	v_mfma_f32_16x16x32_bf16 v[120:123], v[166:169], v[182:185], v[120:123]
	v_mfma_f32_16x16x32_bf16 v[116:119], v[174:177], v[182:185], v[116:119]
	v_mfma_f32_16x16x32_bf16 v[100:103], v[174:177], v[190:193], v[100:103]
	v_mfma_f32_16x16x32_bf16 v[104:107], v[166:169], v[190:193], v[104:107]
	v_mfma_f32_16x16x32_bf16 v[96:99], v[158:161], v[190:193], v[96:99]
	v_mfma_f32_16x16x32_bf16 v[108:111], v[150:153], v[190:193], v[108:111]
	v_mfma_f32_16x16x32_bf16 v[92:95], v[150:153], v[198:201], v[92:95]
	v_mfma_f32_16x16x32_bf16 v[80:83], v[158:161], v[198:201], v[80:83]
	v_mfma_f32_16x16x32_bf16 v[88:91], v[166:169], v[198:201], v[88:91]
	v_mfma_f32_16x16x32_bf16 v[84:87], v[174:177], v[198:201], v[84:87]
	v_mfma_f32_16x16x32_bf16 v[68:71], v[174:177], v[206:209], v[68:71]
	v_mfma_f32_16x16x32_bf16 v[72:75], v[166:169], v[206:209], v[72:75]
	v_mfma_f32_16x16x32_bf16 v[64:67], v[158:161], v[206:209], v[64:67]
	v_mfma_f32_16x16x32_bf16 v[76:79], v[150:153], v[206:209], v[76:79]
	s_barrier
	s_mov_b32 m0, s77
	v_lshl_add_u64 v[216:217], v[212:213], 0, s[18:19]
	global_load_lds_dwordx4 v[216:217], off
	v_lshl_add_u64 v[216:217], v[212:213], 0, s[20:21]
	s_mov_b32 m0, s78
	s_nop 0
	global_load_lds_dwordx4 v[216:217], off
	v_lshl_add_u64 v[216:217], v[212:213], 0, s[22:23]
	s_mov_b32 m0, s79
	v_lshl_add_u64 v[212:213], v[212:213], 0, s[24:25]
	global_load_lds_dwordx4 v[216:217], off
	s_mov_b32 m0, s80
	s_nop 0
	global_load_lds_dwordx4 v[212:213], off
	v_lshl_add_u64 v[212:213], v[214:215], 0, s[18:19]
	s_mov_b32 m0, s60
	s_nop 0
	global_load_lds_dwordx4 v[212:213], off
	v_lshl_add_u64 v[212:213], v[214:215], 0, s[20:21]
	s_mov_b32 m0, s61
	s_nop 0
	global_load_lds_dwordx4 v[212:213], off
	ds_read_b128 v[178:181], v143 offset:49152
	ds_read_b128 v[182:185], v143 offset:50176
	ds_read_b128 v[186:189], v143 offset:51200
	ds_read_b128 v[190:193], v143 offset:52224
	ds_read_b128 v[194:197], v143 offset:53248
	ds_read_b128 v[198:201], v143 offset:54272
	ds_read_b128 v[202:205], v143 offset:55296
	ds_read_b128 v[206:209], v143 offset:56320
	s_waitcnt vmcnt(8)
	s_waitcnt lgkmcnt(0)
	s_barrier
	s_waitcnt lgkmcnt(0)
	v_mfma_f32_16x16x32_bf16 v[60:63], v[146:149], v[178:181], v[60:63]
	v_mfma_f32_16x16x32_bf16 v[48:51], v[154:157], v[178:181], v[48:51]
	v_mfma_f32_16x16x32_bf16 v[56:59], v[162:165], v[178:181], v[56:59]
	v_mfma_f32_16x16x32_bf16 v[52:55], v[170:173], v[178:181], v[52:55]
	v_mfma_f32_16x16x32_bf16 v[36:39], v[170:173], v[186:189], v[36:39]
	v_mfma_f32_16x16x32_bf16 v[40:43], v[162:165], v[186:189], v[40:43]
	v_mfma_f32_16x16x32_bf16 v[32:35], v[154:157], v[186:189], v[32:35]
	v_mfma_f32_16x16x32_bf16 v[44:47], v[146:149], v[186:189], v[44:47]
	v_mfma_f32_16x16x32_bf16 v[28:31], v[146:149], v[194:197], v[28:31]
	v_mfma_f32_16x16x32_bf16 v[16:19], v[154:157], v[194:197], v[16:19]
	v_mfma_f32_16x16x32_bf16 v[24:27], v[162:165], v[194:197], v[24:27]
	v_mfma_f32_16x16x32_bf16 v[20:23], v[170:173], v[194:197], v[20:23]
	v_mfma_f32_16x16x32_bf16 v[4:7], v[170:173], v[202:205], v[4:7]
	v_mfma_f32_16x16x32_bf16 v[8:11], v[162:165], v[202:205], v[8:11]
	v_mfma_f32_16x16x32_bf16 v[0:3], v[154:157], v[202:205], v[0:3]
	v_mfma_f32_16x16x32_bf16 v[12:15], v[146:149], v[202:205], v[12:15]
	v_mfma_f32_16x16x32_bf16 v[60:63], v[150:153], v[182:185], v[60:63]
	v_mfma_f32_16x16x32_bf16 v[48:51], v[158:161], v[182:185], v[48:51]
	v_mfma_f32_16x16x32_bf16 v[56:59], v[166:169], v[182:185], v[56:59]
	v_mfma_f32_16x16x32_bf16 v[52:55], v[174:177], v[182:185], v[52:55]
	v_mfma_f32_16x16x32_bf16 v[36:39], v[174:177], v[190:193], v[36:39]
	v_mfma_f32_16x16x32_bf16 v[40:43], v[166:169], v[190:193], v[40:43]
	v_mfma_f32_16x16x32_bf16 v[32:35], v[158:161], v[190:193], v[32:35]
	v_mfma_f32_16x16x32_bf16 v[44:47], v[150:153], v[190:193], v[44:47]
	v_mfma_f32_16x16x32_bf16 v[28:31], v[150:153], v[198:201], v[28:31]
	v_mfma_f32_16x16x32_bf16 v[16:19], v[158:161], v[198:201], v[16:19]
	v_mfma_f32_16x16x32_bf16 v[24:27], v[166:169], v[198:201], v[24:27]
	v_mfma_f32_16x16x32_bf16 v[20:23], v[174:177], v[198:201], v[20:23]
	v_mfma_f32_16x16x32_bf16 v[4:7], v[174:177], v[206:209], v[4:7]
	v_mfma_f32_16x16x32_bf16 v[8:11], v[166:169], v[206:209], v[8:11]
	v_mfma_f32_16x16x32_bf16 v[0:3], v[158:161], v[206:209], v[0:3]
	v_mfma_f32_16x16x32_bf16 v[12:15], v[150:153], v[206:209], v[12:15]
	s_barrier
	s_cmp_gt_u32 s29, 13
	s_cbranch_scc0 .LBB0_175
	s_and_b64 vcc, exec, s[26:27]
	s_cbranch_vccz .LBB0_178
	s_barrier

.LBB0_255:
	s_add_i32 s73, s73, 2
	s_mov_b32 s74, s73
	s_ashr_i32 s75, s74, 31
	s_lshl_b64 s[76:77], s[74:75], 7
	s_add_u32 s75, s76, 0x100
	s_addc_u32 s78, s77, 0
	s_add_u32 s79, s40, s75
	s_addc_u32 s80, s41, s78
	s_add_u32 s81, s38, s75
	s_addc_u32 s78, s39, s78
	s_cmp_eq_u32 s74, 42
	s_cselect_b32 s75, s1, s80
	s_cselect_b32 s74, s0, s79
	s_cselect_b32 s79, s43, s78
	s_cselect_b32 s78, s42, s81
	v_lshl_add_u64 v[208:209], v[136:137], 0, s[76:77]
	v_lshl_add_u64 v[212:213], v[208:209], 0, s[20:21]
	s_add_i32 m0, s53, 0xc000
	s_nop 0
	global_load_lds_dwordx4 v[212:213], off
	v_lshl_add_u64 v[208:209], v[208:209], 0, s[22:23]
	s_add_i32 m0, s53, 0xe000
	s_nop 0
	global_load_lds_dwordx4 v[208:209], off
	ds_read_b128 v[144:147], v141
	ds_read_b128 v[148:151], v141 offset:1024
	ds_read_b128 v[152:155], v141 offset:2048
	ds_read_b128 v[156:159], v141 offset:3072
	ds_read_b128 v[160:163], v142
	ds_read_b128 v[164:167], v142 offset:1024
	ds_read_b128 v[168:171], v142 offset:2048
	ds_read_b128 v[172:175], v142 offset:3072
	ds_read_b128 v[176:179], v143
	ds_read_b128 v[180:183], v143 offset:1024
	ds_read_b128 v[184:187], v143 offset:2048
	ds_read_b128 v[188:191], v143 offset:3072
	ds_read_b128 v[192:195], v143 offset:4096
	ds_read_b128 v[196:199], v143 offset:5120
	ds_read_b128 v[200:203], v143 offset:6144
	ds_read_b128 v[204:207], v143 offset:7168
	s_waitcnt vmcnt(8)
	s_waitcnt lgkmcnt(0)
	s_barrier
	s_waitcnt lgkmcnt(0)
	v_mfma_f32_16x16x32_bf16 v[124:127], v[144:147], v[176:179], v[124:127]
	v_mfma_f32_16x16x32_bf16 v[120:123], v[152:155], v[176:179], v[120:123]
	v_mfma_f32_16x16x32_bf16 v[108:111], v[160:163], v[176:179], v[108:111]
	v_mfma_f32_16x16x32_bf16 v[104:107], v[168:171], v[176:179], v[104:107]
	v_mfma_f32_16x16x32_bf16 v[88:91], v[168:171], v[184:187], v[88:91]
	v_mfma_f32_16x16x32_bf16 v[92:95], v[160:163], v[184:187], v[92:95]
	v_mfma_f32_16x16x32_bf16 v[112:115], v[152:155], v[184:187], v[112:115]
	v_mfma_f32_16x16x32_bf16 v[116:119], v[144:147], v[184:187], v[116:119]
	v_mfma_f32_16x16x32_bf16 v[100:103], v[144:147], v[192:195], v[100:103]
	v_mfma_f32_16x16x32_bf16 v[96:99], v[152:155], v[192:195], v[96:99]
	v_mfma_f32_16x16x32_bf16 v[76:79], v[160:163], v[192:195], v[76:79]
	v_mfma_f32_16x16x32_bf16 v[72:75], v[168:171], v[192:195], v[72:75]
	v_mfma_f32_16x16x32_bf16 v[64:67], v[168:171], v[200:203], v[64:67]
	v_mfma_f32_16x16x32_bf16 v[68:71], v[160:163], v[200:203], v[68:71]
	v_mfma_f32_16x16x32_bf16 v[80:83], v[152:155], v[200:203], v[80:83]
	v_mfma_f32_16x16x32_bf16 v[84:87], v[144:147], v[200:203], v[84:87]
	v_mfma_f32_16x16x32_bf16 v[124:127], v[148:151], v[180:183], v[124:127]
	v_mfma_f32_16x16x32_bf16 v[120:123], v[156:159], v[180:183], v[120:123]
	v_mfma_f32_16x16x32_bf16 v[108:111], v[164:167], v[180:183], v[108:111]
	v_mfma_f32_16x16x32_bf16 v[104:107], v[172:175], v[180:183], v[104:107]
	v_mfma_f32_16x16x32_bf16 v[88:91], v[172:175], v[188:191], v[88:91]
	v_mfma_f32_16x16x32_bf16 v[92:95], v[164:167], v[188:191], v[92:95]
	v_mfma_f32_16x16x32_bf16 v[112:115], v[156:159], v[188:191], v[112:115]
	v_mfma_f32_16x16x32_bf16 v[116:119], v[148:151], v[188:191], v[116:119]
	v_mfma_f32_16x16x32_bf16 v[100:103], v[148:151], v[196:199], v[100:103]
	v_mfma_f32_16x16x32_bf16 v[96:99], v[156:159], v[196:199], v[96:99]
	v_mfma_f32_16x16x32_bf16 v[76:79], v[164:167], v[196:199], v[76:79]
	v_mfma_f32_16x16x32_bf16 v[72:75], v[172:175], v[196:199], v[72:75]
	v_mfma_f32_16x16x32_bf16 v[64:67], v[172:175], v[204:207], v[64:67]
	v_mfma_f32_16x16x32_bf16 v[68:71], v[164:167], v[204:207], v[68:71]
	v_mfma_f32_16x16x32_bf16 v[80:83], v[156:159], v[204:207], v[80:83]
	v_mfma_f32_16x16x32_bf16 v[84:87], v[148:151], v[204:207], v[84:87]
	s_barrier
	s_add_i32 s76, s63, s52
	v_lshl_add_u64 v[208:209], s[78:79], 0, v[130:131]
	s_mov_b32 m0, s76
	s_nop 0
	global_load_lds_dwordx4 v[208:209], off
	v_lshl_add_u64 v[212:213], v[208:209], 0, s[2:3]
	s_add_i32 m0, s76, 0x2000
	s_add_i32 s76, s64, s52
	global_load_lds_dwordx4 v[212:213], off
	v_lshl_add_u64 v[212:213], v[208:209], 0, s[8:9]
	s_mov_b32 m0, s76
	s_nop 0
	global_load_lds_dwordx4 v[212:213], off
	v_lshl_add_u64 v[212:213], v[208:209], 0, s[14:15]
	s_add_i32 m0, s76, 0x2000
	s_nop 0
	global_load_lds_dwordx4 v[212:213], off
	v_lshl_add_u64 v[212:213], s[74:75], 0, v[128:129]
	s_mov_b32 m0, s53
	v_lshl_add_u64 v[214:215], v[212:213], 0, s[2:3]
	global_load_lds_dwordx4 v[212:213], off
	s_mov_b32 m0, s54
	s_nop 0
	global_load_lds_dwordx4 v[214:215], off
	ds_read_b128 v[176:179], v143 offset:16384
	ds_read_b128 v[180:183], v143 offset:17408
	ds_read_b128 v[184:187], v143 offset:18432
	ds_read_b128 v[188:191], v143 offset:19456
	ds_read_b128 v[192:195], v143 offset:20480
	ds_read_b128 v[196:199], v143 offset:21504
	ds_read_b128 v[200:203], v143 offset:22528
	ds_read_b128 v[204:207], v143 offset:23552
	s_waitcnt vmcnt(8)
	s_waitcnt lgkmcnt(0)
	s_barrier
	s_waitcnt lgkmcnt(0)
	v_mfma_f32_16x16x32_bf16 v[60:63], v[144:147], v[176:179], v[60:63]
	v_mfma_f32_16x16x32_bf16 v[56:59], v[152:155], v[176:179], v[56:59]
	v_mfma_f32_16x16x32_bf16 v[44:47], v[160:163], v[176:179], v[44:47]
	v_mfma_f32_16x16x32_bf16 v[40:43], v[168:171], v[176:179], v[40:43]
	v_mfma_f32_16x16x32_bf16 v[24:27], v[168:171], v[184:187], v[24:27]
	v_mfma_f32_16x16x32_bf16 v[28:31], v[160:163], v[184:187], v[28:31]
	v_mfma_f32_16x16x32_bf16 v[48:51], v[152:155], v[184:187], v[48:51]
	v_mfma_f32_16x16x32_bf16 v[52:55], v[144:147], v[184:187], v[52:55]
	v_mfma_f32_16x16x32_bf16 v[36:39], v[144:147], v[192:195], v[36:39]
	v_mfma_f32_16x16x32_bf16 v[32:35], v[152:155], v[192:195], v[32:35]
	v_mfma_f32_16x16x32_bf16 v[12:15], v[160:163], v[192:195], v[12:15]
	v_mfma_f32_16x16x32_bf16 v[8:11], v[168:171], v[192:195], v[8:11]
	v_mfma_f32_16x16x32_bf16 v[0:3], v[168:171], v[200:203], v[0:3]
	v_mfma_f32_16x16x32_bf16 v[4:7], v[160:163], v[200:203], v[4:7]
	v_mfma_f32_16x16x32_bf16 v[16:19], v[152:155], v[200:203], v[16:19]
	v_mfma_f32_16x16x32_bf16 v[20:23], v[144:147], v[200:203], v[20:23]
	v_mfma_f32_16x16x32_bf16 v[60:63], v[148:151], v[180:183], v[60:63]
	v_mfma_f32_16x16x32_bf16 v[56:59], v[156:159], v[180:183], v[56:59]
	v_mfma_f32_16x16x32_bf16 v[44:47], v[164:167], v[180:183], v[44:47]
	v_mfma_f32_16x16x32_bf16 v[40:43], v[172:175], v[180:183], v[40:43]
	v_mfma_f32_16x16x32_bf16 v[24:27], v[172:175], v[188:191], v[24:27]
	v_mfma_f32_16x16x32_bf16 v[28:31], v[164:167], v[188:191], v[28:31]
	v_mfma_f32_16x16x32_bf16 v[48:51], v[156:159], v[188:191], v[48:51]
	v_mfma_f32_16x16x32_bf16 v[52:55], v[148:151], v[188:191], v[52:55]
	v_mfma_f32_16x16x32_bf16 v[36:39], v[148:151], v[196:199], v[36:39]
	v_mfma_f32_16x16x32_bf16 v[32:35], v[156:159], v[196:199], v[32:35]
	v_mfma_f32_16x16x32_bf16 v[12:15], v[164:167], v[196:199], v[12:15]
	v_mfma_f32_16x16x32_bf16 v[8:11], v[172:175], v[196:199], v[8:11]
	v_mfma_f32_16x16x32_bf16 v[0:3], v[172:175], v[204:207], v[0:3]
	v_mfma_f32_16x16x32_bf16 v[4:7], v[164:167], v[204:207], v[4:7]
	v_mfma_f32_16x16x32_bf16 v[16:19], v[156:159], v[204:207], v[16:19]
	v_mfma_f32_16x16x32_bf16 v[20:23], v[148:151], v[204:207], v[20:23]
	s_barrier
	s_add_i32 s74, 0, 0x18000
	s_add_i32 s75, 0, 0x1c000
	v_add_u32_e32 v156, s74, v140
	v_add_u32_e32 v172, s75, v140
	s_mov_b32 m0, s55
	v_lshl_add_u64 v[214:215], v[212:213], 0, s[8:9]
	global_load_lds_dwordx4 v[214:215], off
	v_lshl_add_u64 v[214:215], v[212:213], 0, s[14:15]
	s_mov_b32 m0, s56
	s_nop 0
	global_load_lds_dwordx4 v[214:215], off
	ds_read_b128 v[144:147], v156
	ds_read_b128 v[148:151], v156 offset:1024
	ds_read_b128 v[152:155], v156 offset:2048
	ds_read_b128 v[156:159], v156 offset:3072
	ds_read_b128 v[160:163], v172
	ds_read_b128 v[164:167], v172 offset:1024
	ds_read_b128 v[168:171], v172 offset:2048
	ds_read_b128 v[172:175], v172 offset:3072
	ds_read_b128 v[176:179], v143 offset:32768
	ds_read_b128 v[180:183], v143 offset:33792
	ds_read_b128 v[184:187], v143 offset:34816
	ds_read_b128 v[188:191], v143 offset:35840
	ds_read_b128 v[192:195], v143 offset:36864
	ds_read_b128 v[196:199], v143 offset:37888
	ds_read_b128 v[200:203], v143 offset:38912
	ds_read_b128 v[204:207], v143 offset:39936
	s_waitcnt vmcnt(8)
	s_waitcnt lgkmcnt(0)
	s_barrier
	s_waitcnt lgkmcnt(0)
	v_mfma_f32_16x16x32_bf16 v[124:127], v[144:147], v[176:179], v[124:127]
	v_mfma_f32_16x16x32_bf16 v[120:123], v[152:155], v[176:179], v[120:123]
	v_mfma_f32_16x16x32_bf16 v[108:111], v[160:163], v[176:179], v[108:111]
	v_mfma_f32_16x16x32_bf16 v[104:107], v[168:171], v[176:179], v[104:107]
	v_mfma_f32_16x16x32_bf16 v[88:91], v[168:171], v[184:187], v[88:91]
	v_mfma_f32_16x16x32_bf16 v[92:95], v[160:163], v[184:187], v[92:95]
	v_mfma_f32_16x16x32_bf16 v[112:115], v[152:155], v[184:187], v[112:115]
	v_mfma_f32_16x16x32_bf16 v[116:119], v[144:147], v[184:187], v[116:119]
	v_mfma_f32_16x16x32_bf16 v[100:103], v[144:147], v[192:195], v[100:103]
	v_mfma_f32_16x16x32_bf16 v[96:99], v[152:155], v[192:195], v[96:99]
	v_mfma_f32_16x16x32_bf16 v[76:79], v[160:163], v[192:195], v[76:79]
	v_mfma_f32_16x16x32_bf16 v[72:75], v[168:171], v[192:195], v[72:75]
	v_mfma_f32_16x16x32_bf16 v[64:67], v[168:171], v[200:203], v[64:67]
	v_mfma_f32_16x16x32_bf16 v[68:71], v[160:163], v[200:203], v[68:71]
	v_mfma_f32_16x16x32_bf16 v[80:83], v[152:155], v[200:203], v[80:83]
	v_mfma_f32_16x16x32_bf16 v[84:87], v[144:147], v[200:203], v[84:87]
	v_mfma_f32_16x16x32_bf16 v[124:127], v[148:151], v[180:183], v[124:127]
	v_mfma_f32_16x16x32_bf16 v[120:123], v[156:159], v[180:183], v[120:123]
	v_mfma_f32_16x16x32_bf16 v[108:111], v[164:167], v[180:183], v[108:111]
	v_mfma_f32_16x16x32_bf16 v[104:107], v[172:175], v[180:183], v[104:107]
	v_mfma_f32_16x16x32_bf16 v[88:91], v[172:175], v[188:191], v[88:91]
	v_mfma_f32_16x16x32_bf16 v[92:95], v[164:167], v[188:191], v[92:95]
	v_mfma_f32_16x16x32_bf16 v[112:115], v[156:159], v[188:191], v[112:115]
	v_mfma_f32_16x16x32_bf16 v[116:119], v[148:151], v[188:191], v[116:119]
	v_mfma_f32_16x16x32_bf16 v[100:103], v[148:151], v[196:199], v[100:103]
	v_mfma_f32_16x16x32_bf16 v[96:99], v[156:159], v[196:199], v[96:99]
	v_mfma_f32_16x16x32_bf16 v[76:79], v[164:167], v[196:199], v[76:79]
	v_mfma_f32_16x16x32_bf16 v[72:75], v[172:175], v[196:199], v[72:75]
	v_mfma_f32_16x16x32_bf16 v[64:67], v[172:175], v[204:207], v[64:67]
	v_mfma_f32_16x16x32_bf16 v[68:71], v[164:167], v[204:207], v[68:71]
	v_mfma_f32_16x16x32_bf16 v[80:83], v[156:159], v[204:207], v[80:83]
	v_mfma_f32_16x16x32_bf16 v[84:87], v[148:151], v[204:207], v[84:87]
	s_barrier
	s_add_i32 s74, s74, s52
	v_lshl_add_u64 v[214:215], v[208:209], 0, s[20:21]
	s_mov_b32 m0, s74
	s_nop 0
	global_load_lds_dwordx4 v[214:215], off
	v_lshl_add_u64 v[214:215], v[208:209], 0, s[22:23]
	s_add_i32 m0, s74, 0x2000
	s_add_i32 s74, s75, s52
	global_load_lds_dwordx4 v[214:215], off
	v_lshl_add_u64 v[214:215], v[208:209], 0, s[24:25]
	s_mov_b32 m0, s74
	v_lshl_add_u64 v[208:209], v[208:209], 0, s[26:27]
	global_load_lds_dwordx4 v[214:215], off
	s_add_i32 m0, s74, 0x2000
	s_nop 0
	global_load_lds_dwordx4 v[208:209], off
	v_lshl_add_u64 v[208:209], v[212:213], 0, s[20:21]
	s_mov_b32 m0, s58
	s_nop 0
	global_load_lds_dwordx4 v[208:209], off
	v_lshl_add_u64 v[208:209], v[212:213], 0, s[22:23]
	s_mov_b32 m0, s59
	s_nop 0
	global_load_lds_dwordx4 v[208:209], off
	ds_read_b128 v[176:179], v143 offset:49152
	ds_read_b128 v[180:183], v143 offset:50176
	ds_read_b128 v[184:187], v143 offset:51200
	ds_read_b128 v[188:191], v143 offset:52224
	ds_read_b128 v[192:195], v143 offset:53248
	ds_read_b128 v[196:199], v143 offset:54272
	ds_read_b128 v[200:203], v143 offset:55296
	ds_read_b128 v[204:207], v143 offset:56320
	s_waitcnt vmcnt(8)
	s_waitcnt lgkmcnt(0)
	s_barrier
	s_waitcnt lgkmcnt(0)
	v_mfma_f32_16x16x32_bf16 v[60:63], v[144:147], v[176:179], v[60:63]
	v_mfma_f32_16x16x32_bf16 v[56:59], v[152:155], v[176:179], v[56:59]
	v_mfma_f32_16x16x32_bf16 v[44:47], v[160:163], v[176:179], v[44:47]
	v_mfma_f32_16x16x32_bf16 v[40:43], v[168:171], v[176:179], v[40:43]
	v_mfma_f32_16x16x32_bf16 v[24:27], v[168:171], v[184:187], v[24:27]
	v_mfma_f32_16x16x32_bf16 v[28:31], v[160:163], v[184:187], v[28:31]
	v_mfma_f32_16x16x32_bf16 v[48:51], v[152:155], v[184:187], v[48:51]
	v_mfma_f32_16x16x32_bf16 v[52:55], v[144:147], v[184:187], v[52:55]
	v_mfma_f32_16x16x32_bf16 v[36:39], v[144:147], v[192:195], v[36:39]
	v_mfma_f32_16x16x32_bf16 v[32:35], v[152:155], v[192:195], v[32:35]
	v_mfma_f32_16x16x32_bf16 v[12:15], v[160:163], v[192:195], v[12:15]
	v_mfma_f32_16x16x32_bf16 v[8:11], v[168:171], v[192:195], v[8:11]
	v_mfma_f32_16x16x32_bf16 v[0:3], v[168:171], v[200:203], v[0:3]
	v_mfma_f32_16x16x32_bf16 v[4:7], v[160:163], v[200:203], v[4:7]
	v_mfma_f32_16x16x32_bf16 v[16:19], v[152:155], v[200:203], v[16:19]
	v_mfma_f32_16x16x32_bf16 v[20:23], v[144:147], v[200:203], v[20:23]
	v_mfma_f32_16x16x32_bf16 v[60:63], v[148:151], v[180:183], v[60:63]
	v_mfma_f32_16x16x32_bf16 v[56:59], v[156:159], v[180:183], v[56:59]
	v_mfma_f32_16x16x32_bf16 v[44:47], v[164:167], v[180:183], v[44:47]
	v_mfma_f32_16x16x32_bf16 v[40:43], v[172:175], v[180:183], v[40:43]
	v_mfma_f32_16x16x32_bf16 v[24:27], v[172:175], v[188:191], v[24:27]
	v_mfma_f32_16x16x32_bf16 v[28:31], v[164:167], v[188:191], v[28:31]
	v_mfma_f32_16x16x32_bf16 v[48:51], v[156:159], v[188:191], v[48:51]
	v_mfma_f32_16x16x32_bf16 v[52:55], v[148:151], v[188:191], v[52:55]
	v_mfma_f32_16x16x32_bf16 v[36:39], v[148:151], v[196:199], v[36:39]
	v_mfma_f32_16x16x32_bf16 v[32:35], v[156:159], v[196:199], v[32:35]
	v_mfma_f32_16x16x32_bf16 v[12:15], v[164:167], v[196:199], v[12:15]
	v_mfma_f32_16x16x32_bf16 v[8:11], v[172:175], v[196:199], v[8:11]
	v_mfma_f32_16x16x32_bf16 v[0:3], v[172:175], v[204:207], v[0:3]
	v_mfma_f32_16x16x32_bf16 v[4:7], v[164:167], v[204:207], v[4:7]
	v_mfma_f32_16x16x32_bf16 v[16:19], v[156:159], v[204:207], v[16:19]
	v_mfma_f32_16x16x32_bf16 v[20:23], v[148:151], v[204:207], v[20:23]
	s_barrier
	s_cmp_gt_u32 s73, 41
	s_cbranch_scc0 .LBB0_255
	s_and_b64 vcc, exec, s[28:29]
	s_cbranch_vccz .LBB0_258
	s_barrier

.LBB0_386:
	s_add_i32 s70, s70, 2
	s_mov_b32 s42, s70
	s_ashr_i32 s43, s42, 31
	s_lshl_b64 s[72:73], s[42:43], 7
	s_add_u32 s43, s72, 0x100
	s_addc_u32 s71, s73, 0
	s_add_u32 s79, s8, s43
	s_addc_u32 s80, s9, s71
	s_add_u32 s82, s2, s43
	s_addc_u32 s71, s3, s71
	s_add_i32 s83, 0, 0x10000
	s_cmp_eq_u32 s42, 14
	s_cselect_b32 s43, s1, s80
	s_cselect_b32 s42, s57, s79
	s_cselect_b32 s81, s68, s71
	s_cselect_b32 s80, s69, s82
	s_add_i32 s71, 0, 0x14000
	v_add_u32_e32 v140, s83, v220
	v_add_u32_e32 v156, s71, v220
	s_add_u32 s72, s8, s72
	s_addc_u32 s73, s9, s73
	v_lshl_add_u64 v[222:223], s[72:73], 0, v[182:183]
	v_lshl_add_u64 v[224:225], v[222:223], 0, s[14:15]
	s_add_i32 m0, s39, 0xc000
	s_nop 0
	global_load_lds_dwordx4 v[224:225], off
	v_lshl_add_u64 v[222:223], v[222:223], 0, s[16:17]
	s_add_i32 m0, s39, 0xe000
	s_nop 0
	global_load_lds_dwordx4 v[222:223], off
	ds_read_b128 v[128:131], v140
	ds_read_b128 v[132:135], v140 offset:1024
	ds_read_b128 v[136:139], v140 offset:2048
	ds_read_b128 v[140:143], v140 offset:3072
	ds_read_b128 v[144:147], v156
	ds_read_b128 v[148:151], v156 offset:1024
	ds_read_b128 v[152:155], v156 offset:2048
	ds_read_b128 v[156:159], v156 offset:3072
	ds_read_b128 v[160:163], v221
	ds_read_b128 v[164:167], v221 offset:1024
	ds_read_b128 v[186:189], v221 offset:2048
	ds_read_b128 v[190:193], v221 offset:3072
	ds_read_b128 v[194:197], v221 offset:4096
	ds_read_b128 v[198:201], v221 offset:5120
	ds_read_b128 v[202:205], v221 offset:6144
	ds_read_b128 v[206:209], v221 offset:7168
	s_waitcnt vmcnt(8)
	s_waitcnt lgkmcnt(0)
	s_barrier
	s_waitcnt lgkmcnt(0)
	v_mfma_f32_16x16x32_bf16 v[124:127], v[128:131], v[160:163], v[124:127]
	v_mfma_f32_16x16x32_bf16 v[120:123], v[136:139], v[160:163], v[120:123]
	v_mfma_f32_16x16x32_bf16 v[116:119], v[144:147], v[160:163], v[116:119]
	v_mfma_f32_16x16x32_bf16 v[108:111], v[152:155], v[160:163], v[108:111]
	v_mfma_f32_16x16x32_bf16 v[92:95], v[152:155], v[186:189], v[92:95]
	v_mfma_f32_16x16x32_bf16 v[100:103], v[144:147], v[186:189], v[100:103]
	v_mfma_f32_16x16x32_bf16 v[104:107], v[136:139], v[186:189], v[104:107]
	v_mfma_f32_16x16x32_bf16 v[112:115], v[128:131], v[186:189], v[112:115]
	v_mfma_f32_16x16x32_bf16 v[96:99], v[128:131], v[194:197], v[96:99]
	v_mfma_f32_16x16x32_bf16 v[88:91], v[136:139], v[194:197], v[88:91]
	v_mfma_f32_16x16x32_bf16 v[84:87], v[144:147], v[194:197], v[84:87]
	v_mfma_f32_16x16x32_bf16 v[76:79], v[152:155], v[194:197], v[76:79]
	v_mfma_f32_16x16x32_bf16 v[64:67], v[152:155], v[202:205], v[64:67]
	v_mfma_f32_16x16x32_bf16 v[68:71], v[144:147], v[202:205], v[68:71]
	v_mfma_f32_16x16x32_bf16 v[72:75], v[136:139], v[202:205], v[72:75]
	v_mfma_f32_16x16x32_bf16 v[80:83], v[128:131], v[202:205], v[80:83]
	v_mfma_f32_16x16x32_bf16 v[124:127], v[132:135], v[164:167], v[124:127]
	v_mfma_f32_16x16x32_bf16 v[120:123], v[140:143], v[164:167], v[120:123]
	v_mfma_f32_16x16x32_bf16 v[116:119], v[148:151], v[164:167], v[116:119]
	v_mfma_f32_16x16x32_bf16 v[108:111], v[156:159], v[164:167], v[108:111]
	v_mfma_f32_16x16x32_bf16 v[92:95], v[156:159], v[190:193], v[92:95]
	v_mfma_f32_16x16x32_bf16 v[100:103], v[148:151], v[190:193], v[100:103]
	v_mfma_f32_16x16x32_bf16 v[104:107], v[140:143], v[190:193], v[104:107]
	v_mfma_f32_16x16x32_bf16 v[112:115], v[132:135], v[190:193], v[112:115]
	v_mfma_f32_16x16x32_bf16 v[96:99], v[132:135], v[198:201], v[96:99]
	v_mfma_f32_16x16x32_bf16 v[88:91], v[140:143], v[198:201], v[88:91]
	v_mfma_f32_16x16x32_bf16 v[84:87], v[148:151], v[198:201], v[84:87]
	v_mfma_f32_16x16x32_bf16 v[76:79], v[156:159], v[198:201], v[76:79]
	v_mfma_f32_16x16x32_bf16 v[64:67], v[156:159], v[206:209], v[64:67]
	v_mfma_f32_16x16x32_bf16 v[68:71], v[148:151], v[206:209], v[68:71]
	v_mfma_f32_16x16x32_bf16 v[72:75], v[140:143], v[206:209], v[72:75]
	v_mfma_f32_16x16x32_bf16 v[80:83], v[132:135], v[206:209], v[80:83]
	s_barrier
	s_add_i32 s72, s83, s74
	v_lshl_add_u64 v[222:223], s[80:81], 0, v[184:185]
	s_mov_b32 m0, s72
	s_nop 0
	global_load_lds_dwordx4 v[222:223], off
	v_lshl_add_u64 v[224:225], v[222:223], 0, s[40:41]
	s_add_i32 m0, s72, 0x2000
	s_add_i32 s71, s71, s74
	global_load_lds_dwordx4 v[224:225], off
	v_lshl_add_u64 v[224:225], v[222:223], 0, s[4:5]
	s_mov_b32 m0, s71
	s_nop 0
	global_load_lds_dwordx4 v[224:225], off
	v_lshl_add_u64 v[224:225], v[222:223], 0, s[6:7]
	s_add_i32 m0, s71, 0x2000
	s_nop 0
	global_load_lds_dwordx4 v[224:225], off
	v_lshl_add_u64 v[224:225], s[42:43], 0, v[182:183]
	s_mov_b32 m0, s39
	v_lshl_add_u64 v[226:227], v[224:225], 0, s[40:41]
	global_load_lds_dwordx4 v[224:225], off
	s_mov_b32 m0, s75
	s_nop 0
	global_load_lds_dwordx4 v[226:227], off
	ds_read_b128 v[160:163], v221 offset:16384
	ds_read_b128 v[164:167], v221 offset:17408
	ds_read_b128 v[186:189], v221 offset:18432
	ds_read_b128 v[190:193], v221 offset:19456
	ds_read_b128 v[194:197], v221 offset:20480
	ds_read_b128 v[198:201], v221 offset:21504
	ds_read_b128 v[202:205], v221 offset:22528
	ds_read_b128 v[206:209], v221 offset:23552
	s_waitcnt vmcnt(8)
	s_waitcnt lgkmcnt(0)
	s_barrier
	s_waitcnt lgkmcnt(0)
	v_mfma_f32_16x16x32_bf16 v[60:63], v[128:131], v[160:163], v[60:63]
	v_mfma_f32_16x16x32_bf16 v[56:59], v[136:139], v[160:163], v[56:59]
	v_mfma_f32_16x16x32_bf16 v[52:55], v[144:147], v[160:163], v[52:55]
	v_mfma_f32_16x16x32_bf16 v[44:47], v[152:155], v[160:163], v[44:47]
	v_mfma_f32_16x16x32_bf16 v[28:31], v[152:155], v[186:189], v[28:31]
	v_mfma_f32_16x16x32_bf16 v[36:39], v[144:147], v[186:189], v[36:39]
	v_mfma_f32_16x16x32_bf16 v[40:43], v[136:139], v[186:189], v[40:43]
	v_mfma_f32_16x16x32_bf16 v[48:51], v[128:131], v[186:189], v[48:51]
	v_mfma_f32_16x16x32_bf16 v[32:35], v[128:131], v[194:197], v[32:35]
	v_mfma_f32_16x16x32_bf16 v[24:27], v[136:139], v[194:197], v[24:27]
	v_mfma_f32_16x16x32_bf16 v[20:23], v[144:147], v[194:197], v[20:23]
	v_mfma_f32_16x16x32_bf16 v[12:15], v[152:155], v[194:197], v[12:15]
	v_mfma_f32_16x16x32_bf16 v[0:3], v[152:155], v[202:205], v[0:3]
	v_mfma_f32_16x16x32_bf16 v[4:7], v[144:147], v[202:205], v[4:7]
	v_mfma_f32_16x16x32_bf16 v[8:11], v[136:139], v[202:205], v[8:11]
	v_mfma_f32_16x16x32_bf16 v[16:19], v[128:131], v[202:205], v[16:19]
	v_mfma_f32_16x16x32_bf16 v[60:63], v[132:135], v[164:167], v[60:63]
	v_mfma_f32_16x16x32_bf16 v[56:59], v[140:143], v[164:167], v[56:59]
	v_mfma_f32_16x16x32_bf16 v[52:55], v[148:151], v[164:167], v[52:55]
	v_mfma_f32_16x16x32_bf16 v[44:47], v[156:159], v[164:167], v[44:47]
	v_mfma_f32_16x16x32_bf16 v[28:31], v[156:159], v[190:193], v[28:31]
	v_mfma_f32_16x16x32_bf16 v[36:39], v[148:151], v[190:193], v[36:39]
	v_mfma_f32_16x16x32_bf16 v[40:43], v[140:143], v[190:193], v[40:43]
	v_mfma_f32_16x16x32_bf16 v[48:51], v[132:135], v[190:193], v[48:51]
	v_mfma_f32_16x16x32_bf16 v[32:35], v[132:135], v[198:201], v[32:35]
	v_mfma_f32_16x16x32_bf16 v[24:27], v[140:143], v[198:201], v[24:27]
	v_mfma_f32_16x16x32_bf16 v[20:23], v[148:151], v[198:201], v[20:23]
	v_mfma_f32_16x16x32_bf16 v[12:15], v[156:159], v[198:201], v[12:15]
	v_mfma_f32_16x16x32_bf16 v[0:3], v[156:159], v[206:209], v[0:3]
	v_mfma_f32_16x16x32_bf16 v[4:7], v[148:151], v[206:209], v[4:7]
	v_mfma_f32_16x16x32_bf16 v[8:11], v[140:143], v[206:209], v[8:11]
	v_mfma_f32_16x16x32_bf16 v[16:19], v[132:135], v[206:209], v[16:19]
	s_barrier
	s_add_i32 s42, 0, 0x18000
	s_add_i32 s43, 0, 0x1c000
	v_add_u32_e32 v140, s42, v220
	v_add_u32_e32 v156, s43, v220
	s_mov_b32 m0, s30
	v_lshl_add_u64 v[226:227], v[224:225], 0, s[4:5]
	global_load_lds_dwordx4 v[226:227], off
	v_lshl_add_u64 v[226:227], v[224:225], 0, s[6:7]
	s_mov_b32 m0, s31
	s_nop 0
	global_load_lds_dwordx4 v[226:227], off
	ds_read_b128 v[128:131], v140
	ds_read_b128 v[132:135], v140 offset:1024
	ds_read_b128 v[136:139], v140 offset:2048
	ds_read_b128 v[140:143], v140 offset:3072
	ds_read_b128 v[144:147], v156
	ds_read_b128 v[148:151], v156 offset:1024
	ds_read_b128 v[152:155], v156 offset:2048
	ds_read_b128 v[156:159], v156 offset:3072
	ds_read_b128 v[160:163], v221 offset:32768
	ds_read_b128 v[164:167], v221 offset:33792
	ds_read_b128 v[186:189], v221 offset:34816
	ds_read_b128 v[190:193], v221 offset:35840
	ds_read_b128 v[194:197], v221 offset:36864
	ds_read_b128 v[198:201], v221 offset:37888
	ds_read_b128 v[202:205], v221 offset:38912
	ds_read_b128 v[206:209], v221 offset:39936
	s_waitcnt vmcnt(8)
	s_waitcnt lgkmcnt(0)
	s_barrier
	s_waitcnt lgkmcnt(0)
	v_mfma_f32_16x16x32_bf16 v[124:127], v[128:131], v[160:163], v[124:127]
	v_mfma_f32_16x16x32_bf16 v[120:123], v[136:139], v[160:163], v[120:123]
	v_mfma_f32_16x16x32_bf16 v[116:119], v[144:147], v[160:163], v[116:119]
	v_mfma_f32_16x16x32_bf16 v[108:111], v[152:155], v[160:163], v[108:111]
	v_mfma_f32_16x16x32_bf16 v[92:95], v[152:155], v[186:189], v[92:95]
	v_mfma_f32_16x16x32_bf16 v[100:103], v[144:147], v[186:189], v[100:103]
	v_mfma_f32_16x16x32_bf16 v[104:107], v[136:139], v[186:189], v[104:107]
	v_mfma_f32_16x16x32_bf16 v[112:115], v[128:131], v[186:189], v[112:115]
	v_mfma_f32_16x16x32_bf16 v[96:99], v[128:131], v[194:197], v[96:99]
	v_mfma_f32_16x16x32_bf16 v[88:91], v[136:139], v[194:197], v[88:91]
	v_mfma_f32_16x16x32_bf16 v[84:87], v[144:147], v[194:197], v[84:87]
	v_mfma_f32_16x16x32_bf16 v[76:79], v[152:155], v[194:197], v[76:79]
	v_mfma_f32_16x16x32_bf16 v[64:67], v[152:155], v[202:205], v[64:67]
	v_mfma_f32_16x16x32_bf16 v[68:71], v[144:147], v[202:205], v[68:71]
	v_mfma_f32_16x16x32_bf16 v[72:75], v[136:139], v[202:205], v[72:75]
	v_mfma_f32_16x16x32_bf16 v[80:83], v[128:131], v[202:205], v[80:83]
	v_mfma_f32_16x16x32_bf16 v[124:127], v[132:135], v[164:167], v[124:127]
	v_mfma_f32_16x16x32_bf16 v[120:123], v[140:143], v[164:167], v[120:123]
	v_mfma_f32_16x16x32_bf16 v[116:119], v[148:151], v[164:167], v[116:119]
	v_mfma_f32_16x16x32_bf16 v[108:111], v[156:159], v[164:167], v[108:111]
	v_mfma_f32_16x16x32_bf16 v[92:95], v[156:159], v[190:193], v[92:95]
	v_mfma_f32_16x16x32_bf16 v[100:103], v[148:151], v[190:193], v[100:103]
	v_mfma_f32_16x16x32_bf16 v[104:107], v[140:143], v[190:193], v[104:107]
	v_mfma_f32_16x16x32_bf16 v[112:115], v[132:135], v[190:193], v[112:115]
	v_mfma_f32_16x16x32_bf16 v[96:99], v[132:135], v[198:201], v[96:99]
	v_mfma_f32_16x16x32_bf16 v[88:91], v[140:143], v[198:201], v[88:91]
	v_mfma_f32_16x16x32_bf16 v[84:87], v[148:151], v[198:201], v[84:87]
	v_mfma_f32_16x16x32_bf16 v[76:79], v[156:159], v[198:201], v[76:79]
	v_mfma_f32_16x16x32_bf16 v[64:67], v[156:159], v[206:209], v[64:67]
	v_mfma_f32_16x16x32_bf16 v[68:71], v[148:151], v[206:209], v[68:71]
	v_mfma_f32_16x16x32_bf16 v[72:75], v[140:143], v[206:209], v[72:75]
	v_mfma_f32_16x16x32_bf16 v[80:83], v[132:135], v[206:209], v[80:83]
	s_barrier
	s_add_i32 s42, s42, s74
	v_lshl_add_u64 v[226:227], v[222:223], 0, s[10:11]
	s_mov_b32 m0, s42
	s_nop 0
	global_load_lds_dwordx4 v[226:227], off
	v_lshl_add_u64 v[226:227], v[222:223], 0, s[12:13]
	s_add_i32 m0, s42, 0x2000
	s_add_i32 s42, s43, s74
	global_load_lds_dwordx4 v[226:227], off
	v_lshl_add_u64 v[226:227], v[222:223], 0, s[14:15]
	s_mov_b32 m0, s42
	v_lshl_add_u64 v[222:223], v[222:223], 0, s[16:17]
	global_load_lds_dwordx4 v[226:227], off
	s_add_i32 m0, s42, 0x2000
	s_nop 0
	global_load_lds_dwordx4 v[222:223], off
	v_lshl_add_u64 v[222:223], v[224:225], 0, s[10:11]
	s_mov_b32 m0, s26
	s_nop 0
	global_load_lds_dwordx4 v[222:223], off
	v_lshl_add_u64 v[222:223], v[224:225], 0, s[12:13]
	s_mov_b32 m0, s27
	s_nop 0
	global_load_lds_dwordx4 v[222:223], off
	ds_read_b128 v[160:163], v221 offset:49152
	ds_read_b128 v[164:167], v221 offset:50176
	ds_read_b128 v[186:189], v221 offset:51200
	ds_read_b128 v[190:193], v221 offset:52224
	ds_read_b128 v[194:197], v221 offset:53248
	ds_read_b128 v[198:201], v221 offset:54272
	ds_read_b128 v[202:205], v221 offset:55296
	ds_read_b128 v[206:209], v221 offset:56320
	s_waitcnt vmcnt(8)
	s_waitcnt lgkmcnt(0)
	s_barrier
	s_waitcnt lgkmcnt(0)
	v_mfma_f32_16x16x32_bf16 v[60:63], v[128:131], v[160:163], v[60:63]
	v_mfma_f32_16x16x32_bf16 v[56:59], v[136:139], v[160:163], v[56:59]
	v_mfma_f32_16x16x32_bf16 v[52:55], v[144:147], v[160:163], v[52:55]
	v_mfma_f32_16x16x32_bf16 v[44:47], v[152:155], v[160:163], v[44:47]
	v_mfma_f32_16x16x32_bf16 v[28:31], v[152:155], v[186:189], v[28:31]
	v_mfma_f32_16x16x32_bf16 v[36:39], v[144:147], v[186:189], v[36:39]
	v_mfma_f32_16x16x32_bf16 v[40:43], v[136:139], v[186:189], v[40:43]
	v_mfma_f32_16x16x32_bf16 v[48:51], v[128:131], v[186:189], v[48:51]
	v_mfma_f32_16x16x32_bf16 v[32:35], v[128:131], v[194:197], v[32:35]
	v_mfma_f32_16x16x32_bf16 v[24:27], v[136:139], v[194:197], v[24:27]
	v_mfma_f32_16x16x32_bf16 v[20:23], v[144:147], v[194:197], v[20:23]
	v_mfma_f32_16x16x32_bf16 v[12:15], v[152:155], v[194:197], v[12:15]
	v_mfma_f32_16x16x32_bf16 v[0:3], v[152:155], v[202:205], v[0:3]
	v_mfma_f32_16x16x32_bf16 v[4:7], v[144:147], v[202:205], v[4:7]
	v_mfma_f32_16x16x32_bf16 v[8:11], v[136:139], v[202:205], v[8:11]
	v_mfma_f32_16x16x32_bf16 v[16:19], v[128:131], v[202:205], v[16:19]
	v_mfma_f32_16x16x32_bf16 v[60:63], v[132:135], v[164:167], v[60:63]
	v_mfma_f32_16x16x32_bf16 v[56:59], v[140:143], v[164:167], v[56:59]
	v_mfma_f32_16x16x32_bf16 v[52:55], v[148:151], v[164:167], v[52:55]
	v_mfma_f32_16x16x32_bf16 v[44:47], v[156:159], v[164:167], v[44:47]
	v_mfma_f32_16x16x32_bf16 v[28:31], v[156:159], v[190:193], v[28:31]
	v_mfma_f32_16x16x32_bf16 v[36:39], v[148:151], v[190:193], v[36:39]
	v_mfma_f32_16x16x32_bf16 v[40:43], v[140:143], v[190:193], v[40:43]
	v_mfma_f32_16x16x32_bf16 v[48:51], v[132:135], v[190:193], v[48:51]
	v_mfma_f32_16x16x32_bf16 v[32:35], v[132:135], v[198:201], v[32:35]
	v_mfma_f32_16x16x32_bf16 v[24:27], v[140:143], v[198:201], v[24:27]
	v_mfma_f32_16x16x32_bf16 v[20:23], v[148:151], v[198:201], v[20:23]
	v_mfma_f32_16x16x32_bf16 v[12:15], v[156:159], v[198:201], v[12:15]
	v_mfma_f32_16x16x32_bf16 v[0:3], v[156:159], v[206:209], v[0:3]
	v_mfma_f32_16x16x32_bf16 v[4:7], v[148:151], v[206:209], v[4:7]
	v_mfma_f32_16x16x32_bf16 v[8:11], v[140:143], v[206:209], v[8:11]
	v_mfma_f32_16x16x32_bf16 v[16:19], v[132:135], v[206:209], v[16:19]
	s_barrier
	s_cmp_gt_u32 s70, 13
	s_cbranch_scc0 .LBB0_386
	s_and_b64 vcc, exec, s[58:59]
	s_cbranch_vccz .LBB0_389
	s_barrier

.LBB0_760:
	s_add_i32 s78, s78, 2
	s_mov_b32 s50, s78
	s_ashr_i32 s51, s50, 31
	s_lshl_b64 s[80:81], s[50:51], 7
	s_add_u32 s51, s80, 0x100
	s_addc_u32 s79, s81, 0
	s_add_u32 s82, s48, s51
	s_addc_u32 s83, s49, s79
	s_add_u32 s84, s8, s51
	s_addc_u32 s79, s9, s79
	s_add_i32 s85, 0, 0x10000
	s_cmp_eq_u32 s50, 14
	s_cselect_b32 s51, s35, s83
	s_cselect_b32 s50, s76, s82
	s_cselect_b32 s83, s31, s79
	s_cselect_b32 s82, s77, s84
	s_add_i32 s79, 0, 0x14000
	s_add_u32 s80, s48, s80
	s_addc_u32 s81, s49, s81
	v_lshl_add_u64 v[134:135], s[80:81], 0, v[128:129]
	v_lshl_add_u64 v[224:225], v[134:135], 0, s[14:15]
	s_add_i32 m0, s62, 0xc000
	s_nop 0
	global_load_lds_dwordx4 v[224:225], off
	v_lshl_add_u64 v[134:135], v[134:135], 0, s[16:17]
	s_add_i32 m0, s62, 0xe000
	s_nop 0
	global_load_lds_dwordx4 v[134:135], off
	v_add_u32_e32 v134, s85, v137
	ds_read_b128 v[130:133], v134
	ds_read_b128 v[140:143], v134 offset:1024
	ds_read_b128 v[144:147], v134 offset:2048
	ds_read_b128 v[148:151], v134 offset:3072
	v_add_u32_e32 v134, s79, v137
	ds_read_b128 v[152:155], v134
	ds_read_b128 v[156:159], v134 offset:1024
	ds_read_b128 v[160:163], v134 offset:2048
	ds_read_b128 v[164:167], v134 offset:3072
	ds_read_b128 v[182:185], v138
	ds_read_b128 v[186:189], v138 offset:1024
	ds_read_b128 v[190:193], v138 offset:2048
	ds_read_b128 v[194:197], v138 offset:3072
	ds_read_b128 v[198:201], v138 offset:4096
	ds_read_b128 v[202:205], v138 offset:5120
	ds_read_b128 v[206:209], v138 offset:6144
	ds_read_b128 v[220:223], v138 offset:7168
	s_nop 0
	s_waitcnt vmcnt(8)
	s_waitcnt lgkmcnt(0)
	s_barrier
	s_waitcnt lgkmcnt(0)
	v_mfma_f32_16x16x32_bf16 v[124:127], v[130:133], v[182:185], v[124:127]
	v_mfma_f32_16x16x32_bf16 v[120:123], v[144:147], v[182:185], v[120:123]
	v_mfma_f32_16x16x32_bf16 v[116:119], v[152:155], v[182:185], v[116:119]
	v_mfma_f32_16x16x32_bf16 v[112:115], v[160:163], v[182:185], v[112:115]
	v_mfma_f32_16x16x32_bf16 v[96:99], v[160:163], v[190:193], v[96:99]
	v_mfma_f32_16x16x32_bf16 v[100:103], v[152:155], v[190:193], v[100:103]
	v_mfma_f32_16x16x32_bf16 v[104:107], v[144:147], v[190:193], v[104:107]
	v_mfma_f32_16x16x32_bf16 v[108:111], v[130:133], v[190:193], v[108:111]
	v_mfma_f32_16x16x32_bf16 v[92:95], v[130:133], v[198:201], v[92:95]
	v_mfma_f32_16x16x32_bf16 v[88:91], v[144:147], v[198:201], v[88:91]
	v_mfma_f32_16x16x32_bf16 v[84:87], v[152:155], v[198:201], v[84:87]
	v_mfma_f32_16x16x32_bf16 v[80:83], v[160:163], v[198:201], v[80:83]
	v_mfma_f32_16x16x32_bf16 v[64:67], v[160:163], v[206:209], v[64:67]
	v_mfma_f32_16x16x32_bf16 v[68:71], v[152:155], v[206:209], v[68:71]
	v_mfma_f32_16x16x32_bf16 v[72:75], v[144:147], v[206:209], v[72:75]
	v_mfma_f32_16x16x32_bf16 v[76:79], v[130:133], v[206:209], v[76:79]
	v_mfma_f32_16x16x32_bf16 v[124:127], v[140:143], v[186:189], v[124:127]
	v_mfma_f32_16x16x32_bf16 v[120:123], v[148:151], v[186:189], v[120:123]
	v_mfma_f32_16x16x32_bf16 v[116:119], v[156:159], v[186:189], v[116:119]
	v_mfma_f32_16x16x32_bf16 v[112:115], v[164:167], v[186:189], v[112:115]
	v_mfma_f32_16x16x32_bf16 v[96:99], v[164:167], v[194:197], v[96:99]
	v_mfma_f32_16x16x32_bf16 v[100:103], v[156:159], v[194:197], v[100:103]
	v_mfma_f32_16x16x32_bf16 v[104:107], v[148:151], v[194:197], v[104:107]
	v_mfma_f32_16x16x32_bf16 v[108:111], v[140:143], v[194:197], v[108:111]
	v_mfma_f32_16x16x32_bf16 v[92:95], v[140:143], v[202:205], v[92:95]
	v_mfma_f32_16x16x32_bf16 v[88:91], v[148:151], v[202:205], v[88:91]
	v_mfma_f32_16x16x32_bf16 v[84:87], v[156:159], v[202:205], v[84:87]
	v_mfma_f32_16x16x32_bf16 v[80:83], v[164:167], v[202:205], v[80:83]
	v_mfma_f32_16x16x32_bf16 v[64:67], v[164:167], v[220:223], v[64:67]
	v_mfma_f32_16x16x32_bf16 v[68:71], v[156:159], v[220:223], v[68:71]
	v_mfma_f32_16x16x32_bf16 v[72:75], v[148:151], v[220:223], v[72:75]
	v_mfma_f32_16x16x32_bf16 v[76:79], v[140:143], v[220:223], v[76:79]
	s_barrier
	s_add_i32 s80, s85, s59
	v_lshl_add_u64 v[134:135], s[82:83], 0, v[172:173]
	s_mov_b32 m0, s80
	s_nop 0
	global_load_lds_dwordx4 v[134:135], off
	v_lshl_add_u64 v[224:225], v[134:135], 0, s[40:41]
	s_add_i32 m0, s80, 0x2000
	s_add_i32 s79, s79, s59
	global_load_lds_dwordx4 v[224:225], off
	v_lshl_add_u64 v[224:225], v[134:135], 0, s[4:5]
	s_mov_b32 m0, s79
	s_nop 0
	global_load_lds_dwordx4 v[224:225], off
	v_lshl_add_u64 v[224:225], v[134:135], 0, s[6:7]
	s_add_i32 m0, s79, 0x2000
	s_nop 0
	global_load_lds_dwordx4 v[224:225], off
	v_lshl_add_u64 v[224:225], s[50:51], 0, v[128:129]
	s_mov_b32 m0, s62
	v_lshl_add_u64 v[226:227], v[224:225], 0, s[40:41]
	global_load_lds_dwordx4 v[224:225], off
	s_mov_b32 m0, s63
	s_nop 0
	global_load_lds_dwordx4 v[226:227], off
	ds_read_b128 v[182:185], v138 offset:16384
	ds_read_b128 v[186:189], v138 offset:17408
	ds_read_b128 v[190:193], v138 offset:18432
	ds_read_b128 v[194:197], v138 offset:19456
	ds_read_b128 v[198:201], v138 offset:20480
	ds_read_b128 v[202:205], v138 offset:21504
	ds_read_b128 v[206:209], v138 offset:22528
	ds_read_b128 v[220:223], v138 offset:23552
	s_waitcnt vmcnt(8)
	s_waitcnt lgkmcnt(0)
	s_barrier
	s_waitcnt lgkmcnt(0)
	v_mfma_f32_16x16x32_bf16 v[60:63], v[130:133], v[182:185], v[60:63]
	v_mfma_f32_16x16x32_bf16 v[56:59], v[144:147], v[182:185], v[56:59]
	v_mfma_f32_16x16x32_bf16 v[52:55], v[152:155], v[182:185], v[52:55]
	v_mfma_f32_16x16x32_bf16 v[48:51], v[160:163], v[182:185], v[48:51]
	v_mfma_f32_16x16x32_bf16 v[32:35], v[160:163], v[190:193], v[32:35]
	v_mfma_f32_16x16x32_bf16 v[36:39], v[152:155], v[190:193], v[36:39]
	v_mfma_f32_16x16x32_bf16 v[40:43], v[144:147], v[190:193], v[40:43]
	v_mfma_f32_16x16x32_bf16 v[44:47], v[130:133], v[190:193], v[44:47]
	v_mfma_f32_16x16x32_bf16 v[28:31], v[130:133], v[198:201], v[28:31]
	v_mfma_f32_16x16x32_bf16 v[24:27], v[144:147], v[198:201], v[24:27]
	v_mfma_f32_16x16x32_bf16 v[20:23], v[152:155], v[198:201], v[20:23]
	v_mfma_f32_16x16x32_bf16 v[16:19], v[160:163], v[198:201], v[16:19]
	v_mfma_f32_16x16x32_bf16 v[0:3], v[160:163], v[206:209], v[0:3]
	v_mfma_f32_16x16x32_bf16 v[4:7], v[152:155], v[206:209], v[4:7]
	v_mfma_f32_16x16x32_bf16 v[8:11], v[144:147], v[206:209], v[8:11]
	v_mfma_f32_16x16x32_bf16 v[12:15], v[130:133], v[206:209], v[12:15]
	v_mfma_f32_16x16x32_bf16 v[60:63], v[140:143], v[186:189], v[60:63]
	v_mfma_f32_16x16x32_bf16 v[56:59], v[148:151], v[186:189], v[56:59]
	v_mfma_f32_16x16x32_bf16 v[52:55], v[156:159], v[186:189], v[52:55]
	v_mfma_f32_16x16x32_bf16 v[48:51], v[164:167], v[186:189], v[48:51]
	v_mfma_f32_16x16x32_bf16 v[32:35], v[164:167], v[194:197], v[32:35]
	v_mfma_f32_16x16x32_bf16 v[36:39], v[156:159], v[194:197], v[36:39]
	v_mfma_f32_16x16x32_bf16 v[40:43], v[148:151], v[194:197], v[40:43]
	v_mfma_f32_16x16x32_bf16 v[44:47], v[140:143], v[194:197], v[44:47]
	v_mfma_f32_16x16x32_bf16 v[28:31], v[140:143], v[202:205], v[28:31]
	v_mfma_f32_16x16x32_bf16 v[24:27], v[148:151], v[202:205], v[24:27]
	v_mfma_f32_16x16x32_bf16 v[20:23], v[156:159], v[202:205], v[20:23]
	v_mfma_f32_16x16x32_bf16 v[16:19], v[164:167], v[202:205], v[16:19]
	v_mfma_f32_16x16x32_bf16 v[0:3], v[164:167], v[220:223], v[0:3]
	v_mfma_f32_16x16x32_bf16 v[4:7], v[156:159], v[220:223], v[4:7]
	v_mfma_f32_16x16x32_bf16 v[8:11], v[148:151], v[220:223], v[8:11]
	v_mfma_f32_16x16x32_bf16 v[12:15], v[140:143], v[220:223], v[12:15]
	s_barrier
	s_mov_b32 m0, s68
	v_lshl_add_u64 v[226:227], v[224:225], 0, s[4:5]
	global_load_lds_dwordx4 v[226:227], off
	v_lshl_add_u64 v[226:227], v[224:225], 0, s[6:7]
	s_mov_b32 m0, s69
	s_nop 0
	global_load_lds_dwordx4 v[226:227], off
	s_add_i32 s50, 0, 0x18000
	v_add_u32_e32 v139, s50, v137
	s_add_i32 s51, 0, 0x1c000
	ds_read_b128 v[130:133], v139
	ds_read_b128 v[140:143], v139 offset:1024
	ds_read_b128 v[144:147], v139 offset:2048
	ds_read_b128 v[148:151], v139 offset:3072
	v_add_u32_e32 v139, s51, v137
	ds_read_b128 v[152:155], v139
	ds_read_b128 v[156:159], v139 offset:1024
	ds_read_b128 v[160:163], v139 offset:2048
	ds_read_b128 v[164:167], v139 offset:3072
	ds_read_b128 v[182:185], v138 offset:32768
	ds_read_b128 v[186:189], v138 offset:33792
	ds_read_b128 v[190:193], v138 offset:34816
	ds_read_b128 v[194:197], v138 offset:35840
	ds_read_b128 v[198:201], v138 offset:36864
	ds_read_b128 v[202:205], v138 offset:37888
	ds_read_b128 v[206:209], v138 offset:38912
	ds_read_b128 v[220:223], v138 offset:39936
	s_nop 0
	s_waitcnt vmcnt(8)
	s_waitcnt lgkmcnt(0)
	s_barrier
	s_waitcnt lgkmcnt(0)
	v_mfma_f32_16x16x32_bf16 v[124:127], v[130:133], v[182:185], v[124:127]
	v_mfma_f32_16x16x32_bf16 v[120:123], v[144:147], v[182:185], v[120:123]
	v_mfma_f32_16x16x32_bf16 v[116:119], v[152:155], v[182:185], v[116:119]
	v_mfma_f32_16x16x32_bf16 v[112:115], v[160:163], v[182:185], v[112:115]
	v_mfma_f32_16x16x32_bf16 v[96:99], v[160:163], v[190:193], v[96:99]
	v_mfma_f32_16x16x32_bf16 v[100:103], v[152:155], v[190:193], v[100:103]
	v_mfma_f32_16x16x32_bf16 v[104:107], v[144:147], v[190:193], v[104:107]
	v_mfma_f32_16x16x32_bf16 v[108:111], v[130:133], v[190:193], v[108:111]
	v_mfma_f32_16x16x32_bf16 v[92:95], v[130:133], v[198:201], v[92:95]
	v_mfma_f32_16x16x32_bf16 v[88:91], v[144:147], v[198:201], v[88:91]
	v_mfma_f32_16x16x32_bf16 v[84:87], v[152:155], v[198:201], v[84:87]
	v_mfma_f32_16x16x32_bf16 v[80:83], v[160:163], v[198:201], v[80:83]
	v_mfma_f32_16x16x32_bf16 v[64:67], v[160:163], v[206:209], v[64:67]
	v_mfma_f32_16x16x32_bf16 v[68:71], v[152:155], v[206:209], v[68:71]
	v_mfma_f32_16x16x32_bf16 v[72:75], v[144:147], v[206:209], v[72:75]
	v_mfma_f32_16x16x32_bf16 v[76:79], v[130:133], v[206:209], v[76:79]
	v_mfma_f32_16x16x32_bf16 v[124:127], v[140:143], v[186:189], v[124:127]
	v_mfma_f32_16x16x32_bf16 v[120:123], v[148:151], v[186:189], v[120:123]
	v_mfma_f32_16x16x32_bf16 v[116:119], v[156:159], v[186:189], v[116:119]
	v_mfma_f32_16x16x32_bf16 v[112:115], v[164:167], v[186:189], v[112:115]
	v_mfma_f32_16x16x32_bf16 v[96:99], v[164:167], v[194:197], v[96:99]
	v_mfma_f32_16x16x32_bf16 v[100:103], v[156:159], v[194:197], v[100:103]
	v_mfma_f32_16x16x32_bf16 v[104:107], v[148:151], v[194:197], v[104:107]
	v_mfma_f32_16x16x32_bf16 v[108:111], v[140:143], v[194:197], v[108:111]
	v_mfma_f32_16x16x32_bf16 v[92:95], v[140:143], v[202:205], v[92:95]
	v_mfma_f32_16x16x32_bf16 v[88:91], v[148:151], v[202:205], v[88:91]
	v_mfma_f32_16x16x32_bf16 v[84:87], v[156:159], v[202:205], v[84:87]
	v_mfma_f32_16x16x32_bf16 v[80:83], v[164:167], v[202:205], v[80:83]
	v_mfma_f32_16x16x32_bf16 v[64:67], v[164:167], v[220:223], v[64:67]
	v_mfma_f32_16x16x32_bf16 v[68:71], v[156:159], v[220:223], v[68:71]
	v_mfma_f32_16x16x32_bf16 v[72:75], v[148:151], v[220:223], v[72:75]
	v_mfma_f32_16x16x32_bf16 v[76:79], v[140:143], v[220:223], v[76:79]
	s_barrier
	s_add_i32 s50, s50, s59
	v_lshl_add_u64 v[226:227], v[134:135], 0, s[10:11]
	s_mov_b32 m0, s50
	s_nop 0
	global_load_lds_dwordx4 v[226:227], off
	v_lshl_add_u64 v[226:227], v[134:135], 0, s[12:13]
	s_add_i32 m0, s50, 0x2000
	s_add_i32 s50, s51, s59
	global_load_lds_dwordx4 v[226:227], off
	v_lshl_add_u64 v[226:227], v[134:135], 0, s[14:15]
	s_mov_b32 m0, s50
	v_lshl_add_u64 v[134:135], v[134:135], 0, s[16:17]
	global_load_lds_dwordx4 v[226:227], off
	s_add_i32 m0, s50, 0x2000
	s_nop 0
	global_load_lds_dwordx4 v[134:135], off
	v_lshl_add_u64 v[134:135], v[224:225], 0, s[10:11]
	s_mov_b32 m0, s72
	s_nop 0
	global_load_lds_dwordx4 v[134:135], off
	v_lshl_add_u64 v[134:135], v[224:225], 0, s[12:13]
	s_mov_b32 m0, s73
	s_nop 0
	global_load_lds_dwordx4 v[134:135], off
	ds_read_b128 v[182:185], v138 offset:49152
	ds_read_b128 v[186:189], v138 offset:50176
	ds_read_b128 v[190:193], v138 offset:51200
	ds_read_b128 v[194:197], v138 offset:52224
	ds_read_b128 v[198:201], v138 offset:53248
	ds_read_b128 v[202:205], v138 offset:54272
	ds_read_b128 v[206:209], v138 offset:55296
	ds_read_b128 v[220:223], v138 offset:56320
	s_waitcnt vmcnt(8)
	s_waitcnt lgkmcnt(0)
	s_barrier
	s_waitcnt lgkmcnt(0)
	v_mfma_f32_16x16x32_bf16 v[60:63], v[130:133], v[182:185], v[60:63]
	v_mfma_f32_16x16x32_bf16 v[56:59], v[144:147], v[182:185], v[56:59]
	v_mfma_f32_16x16x32_bf16 v[52:55], v[152:155], v[182:185], v[52:55]
	v_mfma_f32_16x16x32_bf16 v[48:51], v[160:163], v[182:185], v[48:51]
	v_mfma_f32_16x16x32_bf16 v[32:35], v[160:163], v[190:193], v[32:35]
	v_mfma_f32_16x16x32_bf16 v[36:39], v[152:155], v[190:193], v[36:39]
	v_mfma_f32_16x16x32_bf16 v[40:43], v[144:147], v[190:193], v[40:43]
	v_mfma_f32_16x16x32_bf16 v[44:47], v[130:133], v[190:193], v[44:47]
	v_mfma_f32_16x16x32_bf16 v[28:31], v[130:133], v[198:201], v[28:31]
	v_mfma_f32_16x16x32_bf16 v[24:27], v[144:147], v[198:201], v[24:27]
	v_mfma_f32_16x16x32_bf16 v[20:23], v[152:155], v[198:201], v[20:23]
	v_mfma_f32_16x16x32_bf16 v[16:19], v[160:163], v[198:201], v[16:19]
	v_mfma_f32_16x16x32_bf16 v[0:3], v[160:163], v[206:209], v[0:3]
	v_mfma_f32_16x16x32_bf16 v[4:7], v[152:155], v[206:209], v[4:7]
	v_mfma_f32_16x16x32_bf16 v[8:11], v[144:147], v[206:209], v[8:11]
	v_mfma_f32_16x16x32_bf16 v[12:15], v[130:133], v[206:209], v[12:15]
	v_mfma_f32_16x16x32_bf16 v[60:63], v[140:143], v[186:189], v[60:63]
	v_mfma_f32_16x16x32_bf16 v[56:59], v[148:151], v[186:189], v[56:59]
	v_mfma_f32_16x16x32_bf16 v[52:55], v[156:159], v[186:189], v[52:55]
	v_mfma_f32_16x16x32_bf16 v[48:51], v[164:167], v[186:189], v[48:51]
	v_mfma_f32_16x16x32_bf16 v[32:35], v[164:167], v[194:197], v[32:35]
	v_mfma_f32_16x16x32_bf16 v[36:39], v[156:159], v[194:197], v[36:39]
	v_mfma_f32_16x16x32_bf16 v[40:43], v[148:151], v[194:197], v[40:43]
	v_mfma_f32_16x16x32_bf16 v[44:47], v[140:143], v[194:197], v[44:47]
	v_mfma_f32_16x16x32_bf16 v[28:31], v[140:143], v[202:205], v[28:31]
	v_mfma_f32_16x16x32_bf16 v[24:27], v[148:151], v[202:205], v[24:27]
	v_mfma_f32_16x16x32_bf16 v[20:23], v[156:159], v[202:205], v[20:23]
	v_mfma_f32_16x16x32_bf16 v[16:19], v[164:167], v[202:205], v[16:19]
	v_mfma_f32_16x16x32_bf16 v[0:3], v[164:167], v[220:223], v[0:3]
	v_mfma_f32_16x16x32_bf16 v[4:7], v[156:159], v[220:223], v[4:7]
	v_mfma_f32_16x16x32_bf16 v[8:11], v[148:151], v[220:223], v[8:11]
	v_mfma_f32_16x16x32_bf16 v[12:15], v[140:143], v[220:223], v[12:15]
	s_barrier
	s_cmp_gt_u32 s78, 13
	s_cbranch_scc0 .LBB0_760
	s_and_b64 vcc, exec, s[28:29]
	s_cbranch_vccz .LBB0_763
	s_barrier

.LBB0_784:
	s_add_i32 s80, s80, 2
	s_mov_b32 s48, s80
	s_ashr_i32 s49, s48, 31
	s_lshl_b64 s[82:83], s[48:49], 7
	s_add_u32 s49, s82, 0x100
	s_addc_u32 s81, s83, 0
	s_add_u32 s84, s42, s49
	s_addc_u32 s85, s43, s81
	s_add_u32 s86, s8, s49
	s_addc_u32 s81, s9, s81
	s_add_i32 s87, 0, 0x10000
	s_cmp_eq_u32 s48, 14
	s_cselect_b32 s49, s39, s85
	s_cselect_b32 s48, s72, s84
	s_cselect_b32 s85, s35, s81
	s_cselect_b32 s84, s73, s86
	s_add_i32 s81, 0, 0x14000
	s_add_u32 s82, s42, s82
	s_addc_u32 s83, s43, s83
	v_lshl_add_u64 v[134:135], s[82:83], 0, v[128:129]
	v_lshl_add_u64 v[224:225], v[134:135], 0, s[14:15]
	s_add_i32 m0, s74, 0xc000
	s_nop 0
	global_load_lds_dwordx4 v[224:225], off
	v_lshl_add_u64 v[134:135], v[134:135], 0, s[16:17]
	s_add_i32 m0, s74, 0xe000
	s_nop 0
	global_load_lds_dwordx4 v[134:135], off
	v_add_u32_e32 v134, s87, v137
	ds_read_b128 v[130:133], v134
	ds_read_b128 v[140:143], v134 offset:1024
	ds_read_b128 v[144:147], v134 offset:2048
	ds_read_b128 v[148:151], v134 offset:3072
	v_add_u32_e32 v134, s81, v137
	ds_read_b128 v[152:155], v134
	ds_read_b128 v[156:159], v134 offset:1024
	ds_read_b128 v[160:163], v134 offset:2048
	ds_read_b128 v[164:167], v134 offset:3072
	ds_read_b128 v[182:185], v138
	ds_read_b128 v[186:189], v138 offset:1024
	ds_read_b128 v[190:193], v138 offset:2048
	ds_read_b128 v[194:197], v138 offset:3072
	ds_read_b128 v[198:201], v138 offset:4096
	ds_read_b128 v[202:205], v138 offset:5120
	ds_read_b128 v[206:209], v138 offset:6144
	ds_read_b128 v[220:223], v138 offset:7168
	s_nop 0
	s_waitcnt vmcnt(8)
	s_waitcnt lgkmcnt(0)
	s_barrier
	s_waitcnt lgkmcnt(0)
	v_mfma_f32_16x16x32_bf16 v[124:127], v[130:133], v[182:185], v[124:127]
	v_mfma_f32_16x16x32_bf16 v[120:123], v[144:147], v[182:185], v[120:123]
	v_mfma_f32_16x16x32_bf16 v[116:119], v[152:155], v[182:185], v[116:119]
	v_mfma_f32_16x16x32_bf16 v[112:115], v[160:163], v[182:185], v[112:115]
	v_mfma_f32_16x16x32_bf16 v[96:99], v[160:163], v[190:193], v[96:99]
	v_mfma_f32_16x16x32_bf16 v[100:103], v[152:155], v[190:193], v[100:103]
	v_mfma_f32_16x16x32_bf16 v[104:107], v[144:147], v[190:193], v[104:107]
	v_mfma_f32_16x16x32_bf16 v[108:111], v[130:133], v[190:193], v[108:111]
	v_mfma_f32_16x16x32_bf16 v[92:95], v[130:133], v[198:201], v[92:95]
	v_mfma_f32_16x16x32_bf16 v[88:91], v[144:147], v[198:201], v[88:91]
	v_mfma_f32_16x16x32_bf16 v[84:87], v[152:155], v[198:201], v[84:87]
	v_mfma_f32_16x16x32_bf16 v[80:83], v[160:163], v[198:201], v[80:83]
	v_mfma_f32_16x16x32_bf16 v[64:67], v[160:163], v[206:209], v[64:67]
	v_mfma_f32_16x16x32_bf16 v[68:71], v[152:155], v[206:209], v[68:71]
	v_mfma_f32_16x16x32_bf16 v[72:75], v[144:147], v[206:209], v[72:75]
	v_mfma_f32_16x16x32_bf16 v[76:79], v[130:133], v[206:209], v[76:79]
	v_mfma_f32_16x16x32_bf16 v[124:127], v[140:143], v[186:189], v[124:127]
	v_mfma_f32_16x16x32_bf16 v[120:123], v[148:151], v[186:189], v[120:123]
	v_mfma_f32_16x16x32_bf16 v[116:119], v[156:159], v[186:189], v[116:119]
	v_mfma_f32_16x16x32_bf16 v[112:115], v[164:167], v[186:189], v[112:115]
	v_mfma_f32_16x16x32_bf16 v[96:99], v[164:167], v[194:197], v[96:99]
	v_mfma_f32_16x16x32_bf16 v[100:103], v[156:159], v[194:197], v[100:103]
	v_mfma_f32_16x16x32_bf16 v[104:107], v[148:151], v[194:197], v[104:107]
	v_mfma_f32_16x16x32_bf16 v[108:111], v[140:143], v[194:197], v[108:111]
	v_mfma_f32_16x16x32_bf16 v[92:95], v[140:143], v[202:205], v[92:95]
	v_mfma_f32_16x16x32_bf16 v[88:91], v[148:151], v[202:205], v[88:91]
	v_mfma_f32_16x16x32_bf16 v[84:87], v[156:159], v[202:205], v[84:87]
	v_mfma_f32_16x16x32_bf16 v[80:83], v[164:167], v[202:205], v[80:83]
	v_mfma_f32_16x16x32_bf16 v[64:67], v[164:167], v[220:223], v[64:67]
	v_mfma_f32_16x16x32_bf16 v[68:71], v[156:159], v[220:223], v[68:71]
	v_mfma_f32_16x16x32_bf16 v[72:75], v[148:151], v[220:223], v[72:75]
	v_mfma_f32_16x16x32_bf16 v[76:79], v[140:143], v[220:223], v[76:79]
	s_barrier
	s_add_i32 s82, s87, s63
	v_lshl_add_u64 v[134:135], s[84:85], 0, v[172:173]
	s_mov_b32 m0, s82
	s_nop 0
	global_load_lds_dwordx4 v[134:135], off
	v_lshl_add_u64 v[224:225], v[134:135], 0, s[40:41]
	s_add_i32 m0, s82, 0x2000
	s_add_i32 s81, s81, s63
	global_load_lds_dwordx4 v[224:225], off
	v_lshl_add_u64 v[224:225], v[134:135], 0, s[4:5]
	s_mov_b32 m0, s81
	s_nop 0
	global_load_lds_dwordx4 v[224:225], off
	v_lshl_add_u64 v[224:225], v[134:135], 0, s[6:7]
	s_add_i32 m0, s81, 0x2000
	s_nop 0
	global_load_lds_dwordx4 v[224:225], off
	v_lshl_add_u64 v[224:225], s[48:49], 0, v[128:129]
	s_mov_b32 m0, s74
	v_lshl_add_u64 v[226:227], v[224:225], 0, s[40:41]
	global_load_lds_dwordx4 v[224:225], off
	s_mov_b32 m0, s75
	s_nop 0
	global_load_lds_dwordx4 v[226:227], off
	ds_read_b128 v[182:185], v138 offset:16384
	ds_read_b128 v[186:189], v138 offset:17408
	ds_read_b128 v[190:193], v138 offset:18432
	ds_read_b128 v[194:197], v138 offset:19456
	ds_read_b128 v[198:201], v138 offset:20480
	ds_read_b128 v[202:205], v138 offset:21504
	ds_read_b128 v[206:209], v138 offset:22528
	ds_read_b128 v[220:223], v138 offset:23552
	s_waitcnt vmcnt(8)
	s_waitcnt lgkmcnt(0)
	s_barrier
	s_waitcnt lgkmcnt(0)
	v_mfma_f32_16x16x32_bf16 v[60:63], v[130:133], v[182:185], v[60:63]
	v_mfma_f32_16x16x32_bf16 v[56:59], v[144:147], v[182:185], v[56:59]
	v_mfma_f32_16x16x32_bf16 v[52:55], v[152:155], v[182:185], v[52:55]
	v_mfma_f32_16x16x32_bf16 v[48:51], v[160:163], v[182:185], v[48:51]
	v_mfma_f32_16x16x32_bf16 v[32:35], v[160:163], v[190:193], v[32:35]
	v_mfma_f32_16x16x32_bf16 v[36:39], v[152:155], v[190:193], v[36:39]
	v_mfma_f32_16x16x32_bf16 v[40:43], v[144:147], v[190:193], v[40:43]
	v_mfma_f32_16x16x32_bf16 v[44:47], v[130:133], v[190:193], v[44:47]
	v_mfma_f32_16x16x32_bf16 v[28:31], v[130:133], v[198:201], v[28:31]
	v_mfma_f32_16x16x32_bf16 v[24:27], v[144:147], v[198:201], v[24:27]
	v_mfma_f32_16x16x32_bf16 v[20:23], v[152:155], v[198:201], v[20:23]
	v_mfma_f32_16x16x32_bf16 v[16:19], v[160:163], v[198:201], v[16:19]
	v_mfma_f32_16x16x32_bf16 v[0:3], v[160:163], v[206:209], v[0:3]
	v_mfma_f32_16x16x32_bf16 v[4:7], v[152:155], v[206:209], v[4:7]
	v_mfma_f32_16x16x32_bf16 v[8:11], v[144:147], v[206:209], v[8:11]
	v_mfma_f32_16x16x32_bf16 v[12:15], v[130:133], v[206:209], v[12:15]
	v_mfma_f32_16x16x32_bf16 v[60:63], v[140:143], v[186:189], v[60:63]
	v_mfma_f32_16x16x32_bf16 v[56:59], v[148:151], v[186:189], v[56:59]
	v_mfma_f32_16x16x32_bf16 v[52:55], v[156:159], v[186:189], v[52:55]
	v_mfma_f32_16x16x32_bf16 v[48:51], v[164:167], v[186:189], v[48:51]
	v_mfma_f32_16x16x32_bf16 v[32:35], v[164:167], v[194:197], v[32:35]
	v_mfma_f32_16x16x32_bf16 v[36:39], v[156:159], v[194:197], v[36:39]
	v_mfma_f32_16x16x32_bf16 v[40:43], v[148:151], v[194:197], v[40:43]
	v_mfma_f32_16x16x32_bf16 v[44:47], v[140:143], v[194:197], v[44:47]
	v_mfma_f32_16x16x32_bf16 v[28:31], v[140:143], v[202:205], v[28:31]
	v_mfma_f32_16x16x32_bf16 v[24:27], v[148:151], v[202:205], v[24:27]
	v_mfma_f32_16x16x32_bf16 v[20:23], v[156:159], v[202:205], v[20:23]
	v_mfma_f32_16x16x32_bf16 v[16:19], v[164:167], v[202:205], v[16:19]
	v_mfma_f32_16x16x32_bf16 v[0:3], v[164:167], v[220:223], v[0:3]
	v_mfma_f32_16x16x32_bf16 v[4:7], v[156:159], v[220:223], v[4:7]
	v_mfma_f32_16x16x32_bf16 v[8:11], v[148:151], v[220:223], v[8:11]
	v_mfma_f32_16x16x32_bf16 v[12:15], v[140:143], v[220:223], v[12:15]
	s_barrier
	s_mov_b32 m0, s76
	v_lshl_add_u64 v[226:227], v[224:225], 0, s[4:5]
	global_load_lds_dwordx4 v[226:227], off
	v_lshl_add_u64 v[226:227], v[224:225], 0, s[6:7]
	s_mov_b32 m0, s77
	s_nop 0
	global_load_lds_dwordx4 v[226:227], off
	s_add_i32 s48, 0, 0x18000
	v_add_u32_e32 v139, s48, v137
	s_add_i32 s49, 0, 0x1c000
	ds_read_b128 v[130:133], v139
	ds_read_b128 v[140:143], v139 offset:1024
	ds_read_b128 v[144:147], v139 offset:2048
	ds_read_b128 v[148:151], v139 offset:3072
	v_add_u32_e32 v139, s49, v137
	ds_read_b128 v[152:155], v139
	ds_read_b128 v[156:159], v139 offset:1024
	ds_read_b128 v[160:163], v139 offset:2048
	ds_read_b128 v[164:167], v139 offset:3072
	ds_read_b128 v[182:185], v138 offset:32768
	ds_read_b128 v[186:189], v138 offset:33792
	ds_read_b128 v[190:193], v138 offset:34816
	ds_read_b128 v[194:197], v138 offset:35840
	ds_read_b128 v[198:201], v138 offset:36864
	ds_read_b128 v[202:205], v138 offset:37888
	ds_read_b128 v[206:209], v138 offset:38912
	ds_read_b128 v[220:223], v138 offset:39936
	s_nop 0
	s_waitcnt vmcnt(8)
	s_waitcnt lgkmcnt(0)
	s_barrier
	s_waitcnt lgkmcnt(0)
	v_mfma_f32_16x16x32_bf16 v[124:127], v[130:133], v[182:185], v[124:127]
	v_mfma_f32_16x16x32_bf16 v[120:123], v[144:147], v[182:185], v[120:123]
	v_mfma_f32_16x16x32_bf16 v[116:119], v[152:155], v[182:185], v[116:119]
	v_mfma_f32_16x16x32_bf16 v[112:115], v[160:163], v[182:185], v[112:115]
	v_mfma_f32_16x16x32_bf16 v[96:99], v[160:163], v[190:193], v[96:99]
	v_mfma_f32_16x16x32_bf16 v[100:103], v[152:155], v[190:193], v[100:103]
	v_mfma_f32_16x16x32_bf16 v[104:107], v[144:147], v[190:193], v[104:107]
	v_mfma_f32_16x16x32_bf16 v[108:111], v[130:133], v[190:193], v[108:111]
	v_mfma_f32_16x16x32_bf16 v[92:95], v[130:133], v[198:201], v[92:95]
	v_mfma_f32_16x16x32_bf16 v[88:91], v[144:147], v[198:201], v[88:91]
	v_mfma_f32_16x16x32_bf16 v[84:87], v[152:155], v[198:201], v[84:87]
	v_mfma_f32_16x16x32_bf16 v[80:83], v[160:163], v[198:201], v[80:83]
	v_mfma_f32_16x16x32_bf16 v[64:67], v[160:163], v[206:209], v[64:67]
	v_mfma_f32_16x16x32_bf16 v[68:71], v[152:155], v[206:209], v[68:71]
	v_mfma_f32_16x16x32_bf16 v[72:75], v[144:147], v[206:209], v[72:75]
	v_mfma_f32_16x16x32_bf16 v[76:79], v[130:133], v[206:209], v[76:79]
	v_mfma_f32_16x16x32_bf16 v[124:127], v[140:143], v[186:189], v[124:127]
	v_mfma_f32_16x16x32_bf16 v[120:123], v[148:151], v[186:189], v[120:123]
	v_mfma_f32_16x16x32_bf16 v[116:119], v[156:159], v[186:189], v[116:119]
	v_mfma_f32_16x16x32_bf16 v[112:115], v[164:167], v[186:189], v[112:115]
	v_mfma_f32_16x16x32_bf16 v[96:99], v[164:167], v[194:197], v[96:99]
	v_mfma_f32_16x16x32_bf16 v[100:103], v[156:159], v[194:197], v[100:103]
	v_mfma_f32_16x16x32_bf16 v[104:107], v[148:151], v[194:197], v[104:107]
	v_mfma_f32_16x16x32_bf16 v[108:111], v[140:143], v[194:197], v[108:111]
	v_mfma_f32_16x16x32_bf16 v[92:95], v[140:143], v[202:205], v[92:95]
	v_mfma_f32_16x16x32_bf16 v[88:91], v[148:151], v[202:205], v[88:91]
	v_mfma_f32_16x16x32_bf16 v[84:87], v[156:159], v[202:205], v[84:87]
	v_mfma_f32_16x16x32_bf16 v[80:83], v[164:167], v[202:205], v[80:83]
	v_mfma_f32_16x16x32_bf16 v[64:67], v[164:167], v[220:223], v[64:67]
	v_mfma_f32_16x16x32_bf16 v[68:71], v[156:159], v[220:223], v[68:71]
	v_mfma_f32_16x16x32_bf16 v[72:75], v[148:151], v[220:223], v[72:75]
	v_mfma_f32_16x16x32_bf16 v[76:79], v[140:143], v[220:223], v[76:79]
	s_barrier
	s_add_i32 s48, s48, s63
	v_lshl_add_u64 v[226:227], v[134:135], 0, s[10:11]
	s_mov_b32 m0, s48
	s_nop 0
	global_load_lds_dwordx4 v[226:227], off
	v_lshl_add_u64 v[226:227], v[134:135], 0, s[12:13]
	s_add_i32 m0, s48, 0x2000
	s_add_i32 s48, s49, s63
	global_load_lds_dwordx4 v[226:227], off
	v_lshl_add_u64 v[226:227], v[134:135], 0, s[14:15]
	s_mov_b32 m0, s48
	v_lshl_add_u64 v[134:135], v[134:135], 0, s[16:17]
	global_load_lds_dwordx4 v[226:227], off
	s_add_i32 m0, s48, 0x2000
	s_nop 0
	global_load_lds_dwordx4 v[134:135], off
	v_lshl_add_u64 v[134:135], v[224:225], 0, s[10:11]
	s_mov_b32 m0, s68
	s_nop 0
	global_load_lds_dwordx4 v[134:135], off
	v_lshl_add_u64 v[134:135], v[224:225], 0, s[12:13]
	s_mov_b32 m0, s69
	s_nop 0
	global_load_lds_dwordx4 v[134:135], off
	ds_read_b128 v[182:185], v138 offset:49152
	ds_read_b128 v[186:189], v138 offset:50176
	ds_read_b128 v[190:193], v138 offset:51200
	ds_read_b128 v[194:197], v138 offset:52224
	ds_read_b128 v[198:201], v138 offset:53248
	ds_read_b128 v[202:205], v138 offset:54272
	ds_read_b128 v[206:209], v138 offset:55296
	ds_read_b128 v[220:223], v138 offset:56320
	s_waitcnt vmcnt(8)
	s_waitcnt lgkmcnt(0)
	s_barrier
	s_waitcnt lgkmcnt(0)
	v_mfma_f32_16x16x32_bf16 v[60:63], v[130:133], v[182:185], v[60:63]
	v_mfma_f32_16x16x32_bf16 v[56:59], v[144:147], v[182:185], v[56:59]
	v_mfma_f32_16x16x32_bf16 v[52:55], v[152:155], v[182:185], v[52:55]
	v_mfma_f32_16x16x32_bf16 v[48:51], v[160:163], v[182:185], v[48:51]
	v_mfma_f32_16x16x32_bf16 v[32:35], v[160:163], v[190:193], v[32:35]
	v_mfma_f32_16x16x32_bf16 v[36:39], v[152:155], v[190:193], v[36:39]
	v_mfma_f32_16x16x32_bf16 v[40:43], v[144:147], v[190:193], v[40:43]
	v_mfma_f32_16x16x32_bf16 v[44:47], v[130:133], v[190:193], v[44:47]
	v_mfma_f32_16x16x32_bf16 v[28:31], v[130:133], v[198:201], v[28:31]
	v_mfma_f32_16x16x32_bf16 v[24:27], v[144:147], v[198:201], v[24:27]
	v_mfma_f32_16x16x32_bf16 v[20:23], v[152:155], v[198:201], v[20:23]
	v_mfma_f32_16x16x32_bf16 v[16:19], v[160:163], v[198:201], v[16:19]
	v_mfma_f32_16x16x32_bf16 v[0:3], v[160:163], v[206:209], v[0:3]
	v_mfma_f32_16x16x32_bf16 v[4:7], v[152:155], v[206:209], v[4:7]
	v_mfma_f32_16x16x32_bf16 v[8:11], v[144:147], v[206:209], v[8:11]
	v_mfma_f32_16x16x32_bf16 v[12:15], v[130:133], v[206:209], v[12:15]
	v_mfma_f32_16x16x32_bf16 v[60:63], v[140:143], v[186:189], v[60:63]
	v_mfma_f32_16x16x32_bf16 v[56:59], v[148:151], v[186:189], v[56:59]
	v_mfma_f32_16x16x32_bf16 v[52:55], v[156:159], v[186:189], v[52:55]
	v_mfma_f32_16x16x32_bf16 v[48:51], v[164:167], v[186:189], v[48:51]
	v_mfma_f32_16x16x32_bf16 v[32:35], v[164:167], v[194:197], v[32:35]
	v_mfma_f32_16x16x32_bf16 v[36:39], v[156:159], v[194:197], v[36:39]
	v_mfma_f32_16x16x32_bf16 v[40:43], v[148:151], v[194:197], v[40:43]
	v_mfma_f32_16x16x32_bf16 v[44:47], v[140:143], v[194:197], v[44:47]
	v_mfma_f32_16x16x32_bf16 v[28:31], v[140:143], v[202:205], v[28:31]
	v_mfma_f32_16x16x32_bf16 v[24:27], v[148:151], v[202:205], v[24:27]
	v_mfma_f32_16x16x32_bf16 v[20:23], v[156:159], v[202:205], v[20:23]
	v_mfma_f32_16x16x32_bf16 v[16:19], v[164:167], v[202:205], v[16:19]
	v_mfma_f32_16x16x32_bf16 v[0:3], v[164:167], v[220:223], v[0:3]
	v_mfma_f32_16x16x32_bf16 v[4:7], v[156:159], v[220:223], v[4:7]
	v_mfma_f32_16x16x32_bf16 v[8:11], v[148:151], v[220:223], v[8:11]
	v_mfma_f32_16x16x32_bf16 v[12:15], v[140:143], v[220:223], v[12:15]
	s_barrier
	s_cmp_gt_u32 s80, 13
	s_cbranch_scc0 .LBB0_784
	s_and_b64 vcc, exec, s[30:31]
	s_cbranch_vccz .LBB0_787
	s_barrier

.LBB0_856:
	s_add_i32 s78, s78, 2
	s_mov_b32 s50, s78
	s_ashr_i32 s51, s50, 31
	s_lshl_b64 s[80:81], s[50:51], 7
	v_lshl_add_u64 v[224:225], v[130:131], 0, s[80:81]
	v_lshl_add_u64 v[226:227], v[224:225], 0, s[10:11]
	s_add_i32 m0, s62, 0xc000
	s_nop 0
	global_load_lds_dwordx4 v[226:227], off
	v_lshl_add_u64 v[224:225], v[224:225], 0, s[12:13]
	s_add_i32 m0, s62, 0xe000
	s_nop 0
	global_load_lds_dwordx4 v[224:225], off
	s_add_u32 s51, s80, 0x100
	s_addc_u32 s79, s81, 0
	s_add_u32 s82, s30, s51
	s_addc_u32 s83, s31, s79
	s_add_u32 s84, s28, s51
	s_addc_u32 s79, s29, s79
	s_add_i32 s85, 0, 0x10000
	s_cmp_eq_u32 s50, 14
	s_cselect_b32 s51, s39, s83
	s_cselect_b32 s50, s76, s82
	v_add_u32_e32 v135, s85, v133
	s_cselect_b32 s83, s35, s79
	s_cselect_b32 s82, s77, s84
	s_add_i32 s79, 0, 0x14000
	ds_read_b128 v[136:139], v135
	ds_read_b128 v[140:143], v135 offset:1024
	ds_read_b128 v[144:147], v135 offset:2048
	ds_read_b128 v[148:151], v135 offset:3072
	v_add_u32_e32 v135, s79, v133
	ds_read_b128 v[152:155], v135
	ds_read_b128 v[156:159], v135 offset:1024
	ds_read_b128 v[160:163], v135 offset:2048
	ds_read_b128 v[164:167], v135 offset:3072
	ds_read_b128 v[182:185], v134
	ds_read_b128 v[186:189], v134 offset:1024
	ds_read_b128 v[190:193], v134 offset:2048
	ds_read_b128 v[194:197], v134 offset:3072
	ds_read_b128 v[198:201], v134 offset:4096
	ds_read_b128 v[202:205], v134 offset:5120
	ds_read_b128 v[206:209], v134 offset:6144
	ds_read_b128 v[220:223], v134 offset:7168
	s_nop 0
	s_waitcnt vmcnt(8)
	s_waitcnt lgkmcnt(0)
	s_barrier
	s_waitcnt lgkmcnt(0)
	v_mfma_f32_16x16x32_bf16 v[124:127], v[136:139], v[182:185], v[124:127]
	v_mfma_f32_16x16x32_bf16 v[120:123], v[144:147], v[182:185], v[120:123]
	v_mfma_f32_16x16x32_bf16 v[108:111], v[152:155], v[182:185], v[108:111]
	v_mfma_f32_16x16x32_bf16 v[104:107], v[160:163], v[182:185], v[104:107]
	v_mfma_f32_16x16x32_bf16 v[88:91], v[160:163], v[190:193], v[88:91]
	v_mfma_f32_16x16x32_bf16 v[92:95], v[152:155], v[190:193], v[92:95]
	v_mfma_f32_16x16x32_bf16 v[112:115], v[144:147], v[190:193], v[112:115]
	v_mfma_f32_16x16x32_bf16 v[116:119], v[136:139], v[190:193], v[116:119]
	v_mfma_f32_16x16x32_bf16 v[100:103], v[136:139], v[198:201], v[100:103]
	v_mfma_f32_16x16x32_bf16 v[96:99], v[144:147], v[198:201], v[96:99]
	v_mfma_f32_16x16x32_bf16 v[76:79], v[152:155], v[198:201], v[76:79]
	v_mfma_f32_16x16x32_bf16 v[72:75], v[160:163], v[198:201], v[72:75]
	v_mfma_f32_16x16x32_bf16 v[64:67], v[160:163], v[206:209], v[64:67]
	v_mfma_f32_16x16x32_bf16 v[68:71], v[152:155], v[206:209], v[68:71]
	v_mfma_f32_16x16x32_bf16 v[80:83], v[144:147], v[206:209], v[80:83]
	v_mfma_f32_16x16x32_bf16 v[84:87], v[136:139], v[206:209], v[84:87]
	v_mfma_f32_16x16x32_bf16 v[124:127], v[140:143], v[186:189], v[124:127]
	v_mfma_f32_16x16x32_bf16 v[120:123], v[148:151], v[186:189], v[120:123]
	v_mfma_f32_16x16x32_bf16 v[108:111], v[156:159], v[186:189], v[108:111]
	v_mfma_f32_16x16x32_bf16 v[104:107], v[164:167], v[186:189], v[104:107]
	v_mfma_f32_16x16x32_bf16 v[88:91], v[164:167], v[194:197], v[88:91]
	v_mfma_f32_16x16x32_bf16 v[92:95], v[156:159], v[194:197], v[92:95]
	v_mfma_f32_16x16x32_bf16 v[112:115], v[148:151], v[194:197], v[112:115]
	v_mfma_f32_16x16x32_bf16 v[116:119], v[140:143], v[194:197], v[116:119]
	v_mfma_f32_16x16x32_bf16 v[100:103], v[140:143], v[202:205], v[100:103]
	v_mfma_f32_16x16x32_bf16 v[96:99], v[148:151], v[202:205], v[96:99]
	v_mfma_f32_16x16x32_bf16 v[76:79], v[156:159], v[202:205], v[76:79]
	v_mfma_f32_16x16x32_bf16 v[72:75], v[164:167], v[202:205], v[72:75]
	v_mfma_f32_16x16x32_bf16 v[64:67], v[164:167], v[220:223], v[64:67]
	v_mfma_f32_16x16x32_bf16 v[68:71], v[156:159], v[220:223], v[68:71]
	v_mfma_f32_16x16x32_bf16 v[80:83], v[148:151], v[220:223], v[80:83]
	v_mfma_f32_16x16x32_bf16 v[84:87], v[140:143], v[220:223], v[84:87]
	s_barrier
	s_add_i32 s80, s85, s59
	v_lshl_add_u64 v[224:225], s[82:83], 0, v[172:173]
	s_mov_b32 m0, s80
	s_nop 0
	global_load_lds_dwordx4 v[224:225], off
	v_lshl_add_u64 v[226:227], v[224:225], 0, s[40:41]
	s_add_i32 m0, s80, 0x2000
	s_add_i32 s79, s79, s59
	global_load_lds_dwordx4 v[226:227], off
	v_lshl_add_u64 v[226:227], v[224:225], 0, s[4:5]
	s_mov_b32 m0, s79
	s_nop 0
	global_load_lds_dwordx4 v[226:227], off
	v_lshl_add_u64 v[226:227], v[224:225], 0, s[6:7]
	s_add_i32 m0, s79, 0x2000
	s_nop 0
	global_load_lds_dwordx4 v[226:227], off
	v_lshl_add_u64 v[226:227], s[50:51], 0, v[128:129]
	s_mov_b32 m0, s62
	v_lshl_add_u64 v[228:229], v[226:227], 0, s[40:41]
	global_load_lds_dwordx4 v[226:227], off
	s_mov_b32 m0, s63
	s_nop 0
	global_load_lds_dwordx4 v[228:229], off
	ds_read_b128 v[182:185], v134 offset:16384
	ds_read_b128 v[186:189], v134 offset:17408
	ds_read_b128 v[190:193], v134 offset:18432
	ds_read_b128 v[194:197], v134 offset:19456
	ds_read_b128 v[198:201], v134 offset:20480
	ds_read_b128 v[202:205], v134 offset:21504
	ds_read_b128 v[206:209], v134 offset:22528
	ds_read_b128 v[220:223], v134 offset:23552
	s_waitcnt vmcnt(8)
	s_waitcnt lgkmcnt(0)
	s_barrier
	s_waitcnt lgkmcnt(0)
	v_mfma_f32_16x16x32_bf16 v[60:63], v[136:139], v[182:185], v[60:63]
	v_mfma_f32_16x16x32_bf16 v[56:59], v[144:147], v[182:185], v[56:59]
	v_mfma_f32_16x16x32_bf16 v[44:47], v[152:155], v[182:185], v[44:47]
	v_mfma_f32_16x16x32_bf16 v[40:43], v[160:163], v[182:185], v[40:43]
	v_mfma_f32_16x16x32_bf16 v[24:27], v[160:163], v[190:193], v[24:27]
	v_mfma_f32_16x16x32_bf16 v[28:31], v[152:155], v[190:193], v[28:31]
	v_mfma_f32_16x16x32_bf16 v[48:51], v[144:147], v[190:193], v[48:51]
	v_mfma_f32_16x16x32_bf16 v[52:55], v[136:139], v[190:193], v[52:55]
	v_mfma_f32_16x16x32_bf16 v[36:39], v[136:139], v[198:201], v[36:39]
	v_mfma_f32_16x16x32_bf16 v[32:35], v[144:147], v[198:201], v[32:35]
	v_mfma_f32_16x16x32_bf16 v[12:15], v[152:155], v[198:201], v[12:15]
	v_mfma_f32_16x16x32_bf16 v[8:11], v[160:163], v[198:201], v[8:11]
	v_mfma_f32_16x16x32_bf16 v[0:3], v[160:163], v[206:209], v[0:3]
	v_mfma_f32_16x16x32_bf16 v[4:7], v[152:155], v[206:209], v[4:7]
	v_mfma_f32_16x16x32_bf16 v[16:19], v[144:147], v[206:209], v[16:19]
	v_mfma_f32_16x16x32_bf16 v[20:23], v[136:139], v[206:209], v[20:23]
	v_mfma_f32_16x16x32_bf16 v[60:63], v[140:143], v[186:189], v[60:63]
	v_mfma_f32_16x16x32_bf16 v[56:59], v[148:151], v[186:189], v[56:59]
	v_mfma_f32_16x16x32_bf16 v[44:47], v[156:159], v[186:189], v[44:47]
	v_mfma_f32_16x16x32_bf16 v[40:43], v[164:167], v[186:189], v[40:43]
	v_mfma_f32_16x16x32_bf16 v[24:27], v[164:167], v[194:197], v[24:27]
	v_mfma_f32_16x16x32_bf16 v[28:31], v[156:159], v[194:197], v[28:31]
	v_mfma_f32_16x16x32_bf16 v[48:51], v[148:151], v[194:197], v[48:51]
	v_mfma_f32_16x16x32_bf16 v[52:55], v[140:143], v[194:197], v[52:55]
	v_mfma_f32_16x16x32_bf16 v[36:39], v[140:143], v[202:205], v[36:39]
	v_mfma_f32_16x16x32_bf16 v[32:35], v[148:151], v[202:205], v[32:35]
	v_mfma_f32_16x16x32_bf16 v[12:15], v[156:159], v[202:205], v[12:15]
	v_mfma_f32_16x16x32_bf16 v[8:11], v[164:167], v[202:205], v[8:11]
	v_mfma_f32_16x16x32_bf16 v[0:3], v[164:167], v[220:223], v[0:3]
	v_mfma_f32_16x16x32_bf16 v[4:7], v[156:159], v[220:223], v[4:7]
	v_mfma_f32_16x16x32_bf16 v[16:19], v[148:151], v[220:223], v[16:19]
	v_mfma_f32_16x16x32_bf16 v[20:23], v[140:143], v[220:223], v[20:23]
	s_barrier
	s_mov_b32 m0, s68
	v_lshl_add_u64 v[228:229], v[226:227], 0, s[4:5]
	global_load_lds_dwordx4 v[228:229], off
	v_lshl_add_u64 v[228:229], v[226:227], 0, s[6:7]
	s_mov_b32 m0, s69
	s_nop 0
	global_load_lds_dwordx4 v[228:229], off
	s_add_i32 s50, 0, 0x18000
	v_add_u32_e32 v135, s50, v133
	s_add_i32 s51, 0, 0x1c000
	ds_read_b128 v[136:139], v135
	ds_read_b128 v[140:143], v135 offset:1024
	ds_read_b128 v[144:147], v135 offset:2048
	ds_read_b128 v[148:151], v135 offset:3072
	v_add_u32_e32 v135, s51, v133
	ds_read_b128 v[152:155], v135
	ds_read_b128 v[156:159], v135 offset:1024
	ds_read_b128 v[160:163], v135 offset:2048
	ds_read_b128 v[164:167], v135 offset:3072
	ds_read_b128 v[182:185], v134 offset:32768
	ds_read_b128 v[186:189], v134 offset:33792
	ds_read_b128 v[190:193], v134 offset:34816
	ds_read_b128 v[194:197], v134 offset:35840
	ds_read_b128 v[198:201], v134 offset:36864
	ds_read_b128 v[202:205], v134 offset:37888
	ds_read_b128 v[206:209], v134 offset:38912
	ds_read_b128 v[220:223], v134 offset:39936
	s_nop 0
	s_waitcnt vmcnt(8)
	s_waitcnt lgkmcnt(0)
	s_barrier
	s_waitcnt lgkmcnt(0)
	v_mfma_f32_16x16x32_bf16 v[124:127], v[136:139], v[182:185], v[124:127]
	v_mfma_f32_16x16x32_bf16 v[120:123], v[144:147], v[182:185], v[120:123]
	v_mfma_f32_16x16x32_bf16 v[108:111], v[152:155], v[182:185], v[108:111]
	v_mfma_f32_16x16x32_bf16 v[104:107], v[160:163], v[182:185], v[104:107]
	v_mfma_f32_16x16x32_bf16 v[88:91], v[160:163], v[190:193], v[88:91]
	v_mfma_f32_16x16x32_bf16 v[92:95], v[152:155], v[190:193], v[92:95]
	v_mfma_f32_16x16x32_bf16 v[112:115], v[144:147], v[190:193], v[112:115]
	v_mfma_f32_16x16x32_bf16 v[116:119], v[136:139], v[190:193], v[116:119]
	v_mfma_f32_16x16x32_bf16 v[100:103], v[136:139], v[198:201], v[100:103]
	v_mfma_f32_16x16x32_bf16 v[96:99], v[144:147], v[198:201], v[96:99]
	v_mfma_f32_16x16x32_bf16 v[76:79], v[152:155], v[198:201], v[76:79]
	v_mfma_f32_16x16x32_bf16 v[72:75], v[160:163], v[198:201], v[72:75]
	v_mfma_f32_16x16x32_bf16 v[64:67], v[160:163], v[206:209], v[64:67]
	v_mfma_f32_16x16x32_bf16 v[68:71], v[152:155], v[206:209], v[68:71]
	v_mfma_f32_16x16x32_bf16 v[80:83], v[144:147], v[206:209], v[80:83]
	v_mfma_f32_16x16x32_bf16 v[84:87], v[136:139], v[206:209], v[84:87]
	v_mfma_f32_16x16x32_bf16 v[124:127], v[140:143], v[186:189], v[124:127]
	v_mfma_f32_16x16x32_bf16 v[120:123], v[148:151], v[186:189], v[120:123]
	v_mfma_f32_16x16x32_bf16 v[108:111], v[156:159], v[186:189], v[108:111]
	v_mfma_f32_16x16x32_bf16 v[104:107], v[164:167], v[186:189], v[104:107]
	v_mfma_f32_16x16x32_bf16 v[88:91], v[164:167], v[194:197], v[88:91]
	v_mfma_f32_16x16x32_bf16 v[92:95], v[156:159], v[194:197], v[92:95]
	v_mfma_f32_16x16x32_bf16 v[112:115], v[148:151], v[194:197], v[112:115]
	v_mfma_f32_16x16x32_bf16 v[116:119], v[140:143], v[194:197], v[116:119]
	v_mfma_f32_16x16x32_bf16 v[100:103], v[140:143], v[202:205], v[100:103]
	v_mfma_f32_16x16x32_bf16 v[96:99], v[148:151], v[202:205], v[96:99]
	v_mfma_f32_16x16x32_bf16 v[76:79], v[156:159], v[202:205], v[76:79]
	v_mfma_f32_16x16x32_bf16 v[72:75], v[164:167], v[202:205], v[72:75]
	v_mfma_f32_16x16x32_bf16 v[64:67], v[164:167], v[220:223], v[64:67]
	v_mfma_f32_16x16x32_bf16 v[68:71], v[156:159], v[220:223], v[68:71]
	v_mfma_f32_16x16x32_bf16 v[80:83], v[148:151], v[220:223], v[80:83]
	v_mfma_f32_16x16x32_bf16 v[84:87], v[140:143], v[220:223], v[84:87]
	s_barrier
	s_add_i32 s50, s50, s59
	v_lshl_add_u64 v[228:229], v[224:225], 0, s[10:11]
	s_mov_b32 m0, s50
	s_nop 0
	global_load_lds_dwordx4 v[228:229], off
	v_lshl_add_u64 v[228:229], v[224:225], 0, s[12:13]
	s_add_i32 m0, s50, 0x2000
	s_add_i32 s50, s51, s59
	global_load_lds_dwordx4 v[228:229], off
	v_lshl_add_u64 v[228:229], v[224:225], 0, s[14:15]
	s_mov_b32 m0, s50
	v_lshl_add_u64 v[224:225], v[224:225], 0, s[16:17]
	global_load_lds_dwordx4 v[228:229], off
	s_add_i32 m0, s50, 0x2000
	s_nop 0
	global_load_lds_dwordx4 v[224:225], off
	v_lshl_add_u64 v[224:225], v[226:227], 0, s[10:11]
	s_mov_b32 m0, s72
	s_nop 0
	global_load_lds_dwordx4 v[224:225], off
	v_lshl_add_u64 v[224:225], v[226:227], 0, s[12:13]
	s_mov_b32 m0, s73
	s_nop 0
	global_load_lds_dwordx4 v[224:225], off
	ds_read_b128 v[182:185], v134 offset:49152
	ds_read_b128 v[186:189], v134 offset:50176
	ds_read_b128 v[190:193], v134 offset:51200
	ds_read_b128 v[194:197], v134 offset:52224
	ds_read_b128 v[198:201], v134 offset:53248
	ds_read_b128 v[202:205], v134 offset:54272
	ds_read_b128 v[206:209], v134 offset:55296
	ds_read_b128 v[220:223], v134 offset:56320
	s_waitcnt vmcnt(8)
	s_waitcnt lgkmcnt(0)
	s_barrier
	s_waitcnt lgkmcnt(0)
	v_mfma_f32_16x16x32_bf16 v[60:63], v[136:139], v[182:185], v[60:63]
	v_mfma_f32_16x16x32_bf16 v[56:59], v[144:147], v[182:185], v[56:59]
	v_mfma_f32_16x16x32_bf16 v[44:47], v[152:155], v[182:185], v[44:47]
	v_mfma_f32_16x16x32_bf16 v[40:43], v[160:163], v[182:185], v[40:43]
	v_mfma_f32_16x16x32_bf16 v[24:27], v[160:163], v[190:193], v[24:27]
	v_mfma_f32_16x16x32_bf16 v[28:31], v[152:155], v[190:193], v[28:31]
	v_mfma_f32_16x16x32_bf16 v[48:51], v[144:147], v[190:193], v[48:51]
	v_mfma_f32_16x16x32_bf16 v[52:55], v[136:139], v[190:193], v[52:55]
	v_mfma_f32_16x16x32_bf16 v[36:39], v[136:139], v[198:201], v[36:39]
	v_mfma_f32_16x16x32_bf16 v[32:35], v[144:147], v[198:201], v[32:35]
	v_mfma_f32_16x16x32_bf16 v[12:15], v[152:155], v[198:201], v[12:15]
	v_mfma_f32_16x16x32_bf16 v[8:11], v[160:163], v[198:201], v[8:11]
	v_mfma_f32_16x16x32_bf16 v[0:3], v[160:163], v[206:209], v[0:3]
	v_mfma_f32_16x16x32_bf16 v[4:7], v[152:155], v[206:209], v[4:7]
	v_mfma_f32_16x16x32_bf16 v[16:19], v[144:147], v[206:209], v[16:19]
	v_mfma_f32_16x16x32_bf16 v[20:23], v[136:139], v[206:209], v[20:23]
	v_mfma_f32_16x16x32_bf16 v[60:63], v[140:143], v[186:189], v[60:63]
	v_mfma_f32_16x16x32_bf16 v[56:59], v[148:151], v[186:189], v[56:59]
	v_mfma_f32_16x16x32_bf16 v[44:47], v[156:159], v[186:189], v[44:47]
	v_mfma_f32_16x16x32_bf16 v[40:43], v[164:167], v[186:189], v[40:43]
	v_mfma_f32_16x16x32_bf16 v[24:27], v[164:167], v[194:197], v[24:27]
	v_mfma_f32_16x16x32_bf16 v[28:31], v[156:159], v[194:197], v[28:31]
	v_mfma_f32_16x16x32_bf16 v[48:51], v[148:151], v[194:197], v[48:51]
	v_mfma_f32_16x16x32_bf16 v[52:55], v[140:143], v[194:197], v[52:55]
	v_mfma_f32_16x16x32_bf16 v[36:39], v[140:143], v[202:205], v[36:39]
	v_mfma_f32_16x16x32_bf16 v[32:35], v[148:151], v[202:205], v[32:35]
	v_mfma_f32_16x16x32_bf16 v[12:15], v[156:159], v[202:205], v[12:15]
	v_mfma_f32_16x16x32_bf16 v[8:11], v[164:167], v[202:205], v[8:11]
	v_mfma_f32_16x16x32_bf16 v[0:3], v[164:167], v[220:223], v[0:3]
	v_mfma_f32_16x16x32_bf16 v[4:7], v[156:159], v[220:223], v[4:7]
	v_mfma_f32_16x16x32_bf16 v[16:19], v[148:151], v[220:223], v[16:19]
	v_mfma_f32_16x16x32_bf16 v[20:23], v[140:143], v[220:223], v[20:23]
	s_barrier
	s_cmp_gt_u32 s78, 13
	s_cbranch_scc0 .LBB0_856
	s_and_b64 vcc, exec, s[8:9]
	s_cbranch_vccz .LBB0_859
	s_barrier

.LBB0_970:
	s_add_i32 s21, s21, 2
	s_mov_b32 s38, s21
	s_ashr_i32 s39, s38, 31
	s_lshl_b64 s[74:75], s[38:39], 7
	s_add_u32 s39, s74, 0x100
	s_addc_u32 s73, s75, 0
	s_add_u32 s76, s34, s39
	s_addc_u32 s77, s35, s73
	s_add_u32 s78, s30, s39
	s_addc_u32 s73, s31, s73
	s_cmp_eq_u32 s38, 14
	s_cselect_b32 s39, s67, s77
	s_cselect_b32 s38, s68, s76
	s_cselect_b32 s77, s23, s73
	s_cselect_b32 s76, s66, s78
	s_add_u32 s74, s34, s74
	s_addc_u32 s75, s35, s75
	v_lshl_add_u64 v[208:209], s[74:75], 0, v[130:131]
	s_mov_b32 m0, s59
	v_lshl_add_u64 v[216:217], v[208:209], 0, s[14:15]
	global_load_lds_dwordx4 v[216:217], off
	v_lshl_add_u64 v[208:209], v[208:209], 0, s[16:17]
	s_mov_b32 m0, s60
	s_nop 0
	global_load_lds_dwordx4 v[208:209], off
	ds_read_b128 v[144:147], v140
	ds_read_b128 v[148:151], v140 offset:1024
	ds_read_b128 v[152:155], v140 offset:2048
	ds_read_b128 v[156:159], v140 offset:3072
	ds_read_b128 v[160:163], v141
	ds_read_b128 v[164:167], v141 offset:1024
	ds_read_b128 v[172:175], v141 offset:2048
	ds_read_b128 v[176:179], v141 offset:3072
	ds_read_b128 v[180:183], v142
	ds_read_b128 v[184:187], v142 offset:1024
	ds_read_b128 v[188:191], v142 offset:2048
	ds_read_b128 v[192:195], v142 offset:3072
	ds_read_b128 v[196:199], v142 offset:4096
	ds_read_b128 v[200:203], v142 offset:5120
	ds_read_b128 v[204:207], v142 offset:6144
	ds_read_b128 v[212:215], v142 offset:7168
	s_waitcnt vmcnt(8)
	s_waitcnt lgkmcnt(0)
	s_barrier
	s_waitcnt lgkmcnt(0)
	v_mfma_f32_16x16x32_bf16 v[124:127], v[144:147], v[180:183], v[124:127]
	v_mfma_f32_16x16x32_bf16 v[112:115], v[152:155], v[180:183], v[112:115]
	v_mfma_f32_16x16x32_bf16 v[120:123], v[160:163], v[180:183], v[120:123]
	v_mfma_f32_16x16x32_bf16 v[116:119], v[172:175], v[180:183], v[116:119]
	v_mfma_f32_16x16x32_bf16 v[100:103], v[172:175], v[188:191], v[100:103]
	v_mfma_f32_16x16x32_bf16 v[104:107], v[160:163], v[188:191], v[104:107]
	v_mfma_f32_16x16x32_bf16 v[96:99], v[152:155], v[188:191], v[96:99]
	v_mfma_f32_16x16x32_bf16 v[108:111], v[144:147], v[188:191], v[108:111]
	v_mfma_f32_16x16x32_bf16 v[92:95], v[144:147], v[196:199], v[92:95]
	v_mfma_f32_16x16x32_bf16 v[80:83], v[152:155], v[196:199], v[80:83]
	v_mfma_f32_16x16x32_bf16 v[88:91], v[160:163], v[196:199], v[88:91]
	v_mfma_f32_16x16x32_bf16 v[84:87], v[172:175], v[196:199], v[84:87]
	v_mfma_f32_16x16x32_bf16 v[68:71], v[172:175], v[204:207], v[68:71]
	v_mfma_f32_16x16x32_bf16 v[72:75], v[160:163], v[204:207], v[72:75]
	v_mfma_f32_16x16x32_bf16 v[64:67], v[152:155], v[204:207], v[64:67]
	v_mfma_f32_16x16x32_bf16 v[76:79], v[144:147], v[204:207], v[76:79]
	v_mfma_f32_16x16x32_bf16 v[124:127], v[148:151], v[184:187], v[124:127]
	v_mfma_f32_16x16x32_bf16 v[112:115], v[156:159], v[184:187], v[112:115]
	v_mfma_f32_16x16x32_bf16 v[120:123], v[164:167], v[184:187], v[120:123]
	v_mfma_f32_16x16x32_bf16 v[116:119], v[176:179], v[184:187], v[116:119]
	v_mfma_f32_16x16x32_bf16 v[100:103], v[176:179], v[192:195], v[100:103]
	v_mfma_f32_16x16x32_bf16 v[104:107], v[164:167], v[192:195], v[104:107]
	v_mfma_f32_16x16x32_bf16 v[96:99], v[156:159], v[192:195], v[96:99]
	v_mfma_f32_16x16x32_bf16 v[108:111], v[148:151], v[192:195], v[108:111]
	v_mfma_f32_16x16x32_bf16 v[92:95], v[148:151], v[200:203], v[92:95]
	v_mfma_f32_16x16x32_bf16 v[80:83], v[156:159], v[200:203], v[80:83]
	v_mfma_f32_16x16x32_bf16 v[88:91], v[164:167], v[200:203], v[88:91]
	v_mfma_f32_16x16x32_bf16 v[84:87], v[176:179], v[200:203], v[84:87]
	v_mfma_f32_16x16x32_bf16 v[68:71], v[176:179], v[212:215], v[68:71]
	v_mfma_f32_16x16x32_bf16 v[72:75], v[164:167], v[212:215], v[72:75]
	v_mfma_f32_16x16x32_bf16 v[64:67], v[156:159], v[212:215], v[64:67]
	v_mfma_f32_16x16x32_bf16 v[76:79], v[148:151], v[212:215], v[76:79]
	s_barrier
	s_mov_b32 m0, s61
	v_lshl_add_u64 v[208:209], s[76:77], 0, v[128:129]
	global_load_lds_dwordx4 v[208:209], off
	v_lshl_add_u64 v[216:217], v[208:209], 0, s[0:1]
	s_mov_b32 m0, s62
	s_nop 0
	global_load_lds_dwordx4 v[216:217], off
	v_lshl_add_u64 v[216:217], v[208:209], 0, s[2:3]
	s_mov_b32 m0, s63
	s_nop 0
	global_load_lds_dwordx4 v[216:217], off
	v_lshl_add_u64 v[216:217], v[208:209], 0, s[4:5]
	s_mov_b32 m0, s64
	s_nop 0
	global_load_lds_dwordx4 v[216:217], off
	v_lshl_add_u64 v[216:217], s[38:39], 0, v[130:131]
	s_mov_b32 m0, s48
	v_lshl_add_u64 v[218:219], v[216:217], 0, s[0:1]
	global_load_lds_dwordx4 v[216:217], off
	s_mov_b32 m0, s49
	s_nop 0
	global_load_lds_dwordx4 v[218:219], off
	ds_read_b128 v[180:183], v142 offset:16384
	ds_read_b128 v[184:187], v142 offset:17408
	ds_read_b128 v[188:191], v142 offset:18432
	ds_read_b128 v[192:195], v142 offset:19456
	ds_read_b128 v[196:199], v142 offset:20480
	ds_read_b128 v[200:203], v142 offset:21504
	ds_read_b128 v[204:207], v142 offset:22528
	ds_read_b128 v[212:215], v142 offset:23552
	s_waitcnt vmcnt(8)
	s_waitcnt lgkmcnt(0)
	s_barrier
	s_waitcnt lgkmcnt(0)
	v_mfma_f32_16x16x32_bf16 v[60:63], v[144:147], v[180:183], v[60:63]
	v_mfma_f32_16x16x32_bf16 v[48:51], v[152:155], v[180:183], v[48:51]
	v_mfma_f32_16x16x32_bf16 v[56:59], v[160:163], v[180:183], v[56:59]
	v_mfma_f32_16x16x32_bf16 v[52:55], v[172:175], v[180:183], v[52:55]
	v_mfma_f32_16x16x32_bf16 v[36:39], v[172:175], v[188:191], v[36:39]
	v_mfma_f32_16x16x32_bf16 v[40:43], v[160:163], v[188:191], v[40:43]
	v_mfma_f32_16x16x32_bf16 v[32:35], v[152:155], v[188:191], v[32:35]
	v_mfma_f32_16x16x32_bf16 v[44:47], v[144:147], v[188:191], v[44:47]
	v_mfma_f32_16x16x32_bf16 v[28:31], v[144:147], v[196:199], v[28:31]
	v_mfma_f32_16x16x32_bf16 v[16:19], v[152:155], v[196:199], v[16:19]
	v_mfma_f32_16x16x32_bf16 v[24:27], v[160:163], v[196:199], v[24:27]
	v_mfma_f32_16x16x32_bf16 v[20:23], v[172:175], v[196:199], v[20:23]
	v_mfma_f32_16x16x32_bf16 v[4:7], v[172:175], v[204:207], v[4:7]
	v_mfma_f32_16x16x32_bf16 v[8:11], v[160:163], v[204:207], v[8:11]
	v_mfma_f32_16x16x32_bf16 v[0:3], v[152:155], v[204:207], v[0:3]
	v_mfma_f32_16x16x32_bf16 v[12:15], v[144:147], v[204:207], v[12:15]
	v_mfma_f32_16x16x32_bf16 v[60:63], v[148:151], v[184:187], v[60:63]
	v_mfma_f32_16x16x32_bf16 v[48:51], v[156:159], v[184:187], v[48:51]
	v_mfma_f32_16x16x32_bf16 v[56:59], v[164:167], v[184:187], v[56:59]
	v_mfma_f32_16x16x32_bf16 v[52:55], v[176:179], v[184:187], v[52:55]
	v_mfma_f32_16x16x32_bf16 v[36:39], v[176:179], v[192:195], v[36:39]
	v_mfma_f32_16x16x32_bf16 v[40:43], v[164:167], v[192:195], v[40:43]
	v_mfma_f32_16x16x32_bf16 v[32:35], v[156:159], v[192:195], v[32:35]
	v_mfma_f32_16x16x32_bf16 v[44:47], v[148:151], v[192:195], v[44:47]
	v_mfma_f32_16x16x32_bf16 v[28:31], v[148:151], v[200:203], v[28:31]
	v_mfma_f32_16x16x32_bf16 v[16:19], v[156:159], v[200:203], v[16:19]
	v_mfma_f32_16x16x32_bf16 v[24:27], v[164:167], v[200:203], v[24:27]
	v_mfma_f32_16x16x32_bf16 v[20:23], v[176:179], v[200:203], v[20:23]
	v_mfma_f32_16x16x32_bf16 v[4:7], v[176:179], v[212:215], v[4:7]
	v_mfma_f32_16x16x32_bf16 v[8:11], v[164:167], v[212:215], v[8:11]
	v_mfma_f32_16x16x32_bf16 v[0:3], v[156:159], v[212:215], v[0:3]
	v_mfma_f32_16x16x32_bf16 v[12:15], v[148:151], v[212:215], v[12:15]
	s_barrier
	s_mov_b32 m0, s50
	v_lshl_add_u64 v[218:219], v[216:217], 0, s[2:3]
	global_load_lds_dwordx4 v[218:219], off
	v_lshl_add_u64 v[218:219], v[216:217], 0, s[4:5]
	s_mov_b32 m0, s51
	s_nop 0
	global_load_lds_dwordx4 v[218:219], off
	ds_read_b128 v[144:147], v143
	ds_read_b128 v[148:151], v143 offset:1024
	ds_read_b128 v[152:155], v143 offset:2048
	ds_read_b128 v[156:159], v143 offset:3072
	ds_read_b128 v[160:163], v136
	ds_read_b128 v[164:167], v136 offset:1024
	ds_read_b128 v[172:175], v136 offset:2048
	ds_read_b128 v[176:179], v136 offset:3072
	ds_read_b128 v[180:183], v142 offset:32768
	ds_read_b128 v[184:187], v142 offset:33792
	ds_read_b128 v[188:191], v142 offset:34816
	ds_read_b128 v[192:195], v142 offset:35840
	ds_read_b128 v[196:199], v142 offset:36864
	ds_read_b128 v[200:203], v142 offset:37888
	ds_read_b128 v[204:207], v142 offset:38912
	ds_read_b128 v[212:215], v142 offset:39936
	s_waitcnt vmcnt(8)
	s_waitcnt lgkmcnt(0)
	s_barrier
	s_waitcnt lgkmcnt(0)
	v_mfma_f32_16x16x32_bf16 v[124:127], v[144:147], v[180:183], v[124:127]
	v_mfma_f32_16x16x32_bf16 v[112:115], v[152:155], v[180:183], v[112:115]
	v_mfma_f32_16x16x32_bf16 v[120:123], v[160:163], v[180:183], v[120:123]
	v_mfma_f32_16x16x32_bf16 v[116:119], v[172:175], v[180:183], v[116:119]
	v_mfma_f32_16x16x32_bf16 v[100:103], v[172:175], v[188:191], v[100:103]
	v_mfma_f32_16x16x32_bf16 v[104:107], v[160:163], v[188:191], v[104:107]
	v_mfma_f32_16x16x32_bf16 v[96:99], v[152:155], v[188:191], v[96:99]
	v_mfma_f32_16x16x32_bf16 v[108:111], v[144:147], v[188:191], v[108:111]
	v_mfma_f32_16x16x32_bf16 v[92:95], v[144:147], v[196:199], v[92:95]
	v_mfma_f32_16x16x32_bf16 v[80:83], v[152:155], v[196:199], v[80:83]
	v_mfma_f32_16x16x32_bf16 v[88:91], v[160:163], v[196:199], v[88:91]
	v_mfma_f32_16x16x32_bf16 v[84:87], v[172:175], v[196:199], v[84:87]
	v_mfma_f32_16x16x32_bf16 v[68:71], v[172:175], v[204:207], v[68:71]
	v_mfma_f32_16x16x32_bf16 v[72:75], v[160:163], v[204:207], v[72:75]
	v_mfma_f32_16x16x32_bf16 v[64:67], v[152:155], v[204:207], v[64:67]
	v_mfma_f32_16x16x32_bf16 v[76:79], v[144:147], v[204:207], v[76:79]
	v_mfma_f32_16x16x32_bf16 v[124:127], v[148:151], v[184:187], v[124:127]
	v_mfma_f32_16x16x32_bf16 v[112:115], v[156:159], v[184:187], v[112:115]
	v_mfma_f32_16x16x32_bf16 v[120:123], v[164:167], v[184:187], v[120:123]
	v_mfma_f32_16x16x32_bf16 v[116:119], v[176:179], v[184:187], v[116:119]
	v_mfma_f32_16x16x32_bf16 v[100:103], v[176:179], v[192:195], v[100:103]
	v_mfma_f32_16x16x32_bf16 v[104:107], v[164:167], v[192:195], v[104:107]
	v_mfma_f32_16x16x32_bf16 v[96:99], v[156:159], v[192:195], v[96:99]
	v_mfma_f32_16x16x32_bf16 v[108:111], v[148:151], v[192:195], v[108:111]
	v_mfma_f32_16x16x32_bf16 v[92:95], v[148:151], v[200:203], v[92:95]
	v_mfma_f32_16x16x32_bf16 v[80:83], v[156:159], v[200:203], v[80:83]
	v_mfma_f32_16x16x32_bf16 v[88:91], v[164:167], v[200:203], v[88:91]
	v_mfma_f32_16x16x32_bf16 v[84:87], v[176:179], v[200:203], v[84:87]
	v_mfma_f32_16x16x32_bf16 v[68:71], v[176:179], v[212:215], v[68:71]
	v_mfma_f32_16x16x32_bf16 v[72:75], v[164:167], v[212:215], v[72:75]
	v_mfma_f32_16x16x32_bf16 v[64:67], v[156:159], v[212:215], v[64:67]
	v_mfma_f32_16x16x32_bf16 v[76:79], v[148:151], v[212:215], v[76:79]
	s_barrier
	s_mov_b32 m0, s69
	v_lshl_add_u64 v[218:219], v[208:209], 0, s[10:11]
	global_load_lds_dwordx4 v[218:219], off
	v_lshl_add_u64 v[218:219], v[208:209], 0, s[12:13]
	s_mov_b32 m0, s70
	s_nop 0
	global_load_lds_dwordx4 v[218:219], off
	v_lshl_add_u64 v[218:219], v[208:209], 0, s[14:15]
	s_mov_b32 m0, s71
	v_lshl_add_u64 v[208:209], v[208:209], 0, s[16:17]
	global_load_lds_dwordx4 v[218:219], off
	s_mov_b32 m0, s72
	s_nop 0
	global_load_lds_dwordx4 v[208:209], off
	v_lshl_add_u64 v[208:209], v[216:217], 0, s[10:11]
	s_mov_b32 m0, s53
	s_nop 0
	global_load_lds_dwordx4 v[208:209], off
	v_lshl_add_u64 v[208:209], v[216:217], 0, s[12:13]
	s_mov_b32 m0, s54
	s_nop 0
	global_load_lds_dwordx4 v[208:209], off
	ds_read_b128 v[180:183], v142 offset:49152
	ds_read_b128 v[184:187], v142 offset:50176
	ds_read_b128 v[188:191], v142 offset:51200
	ds_read_b128 v[192:195], v142 offset:52224
	ds_read_b128 v[196:199], v142 offset:53248
	ds_read_b128 v[200:203], v142 offset:54272
	ds_read_b128 v[204:207], v142 offset:55296
	ds_read_b128 v[212:215], v142 offset:56320
	s_waitcnt vmcnt(8)
	s_waitcnt lgkmcnt(0)
	s_barrier
	s_waitcnt lgkmcnt(0)
	v_mfma_f32_16x16x32_bf16 v[60:63], v[144:147], v[180:183], v[60:63]
	v_mfma_f32_16x16x32_bf16 v[48:51], v[152:155], v[180:183], v[48:51]
	v_mfma_f32_16x16x32_bf16 v[56:59], v[160:163], v[180:183], v[56:59]
	v_mfma_f32_16x16x32_bf16 v[52:55], v[172:175], v[180:183], v[52:55]
	v_mfma_f32_16x16x32_bf16 v[36:39], v[172:175], v[188:191], v[36:39]
	v_mfma_f32_16x16x32_bf16 v[40:43], v[160:163], v[188:191], v[40:43]
	v_mfma_f32_16x16x32_bf16 v[32:35], v[152:155], v[188:191], v[32:35]
	v_mfma_f32_16x16x32_bf16 v[44:47], v[144:147], v[188:191], v[44:47]
	v_mfma_f32_16x16x32_bf16 v[28:31], v[144:147], v[196:199], v[28:31]
	v_mfma_f32_16x16x32_bf16 v[16:19], v[152:155], v[196:199], v[16:19]
	v_mfma_f32_16x16x32_bf16 v[24:27], v[160:163], v[196:199], v[24:27]
	v_mfma_f32_16x16x32_bf16 v[20:23], v[172:175], v[196:199], v[20:23]
	v_mfma_f32_16x16x32_bf16 v[4:7], v[172:175], v[204:207], v[4:7]
	v_mfma_f32_16x16x32_bf16 v[8:11], v[160:163], v[204:207], v[8:11]
	v_mfma_f32_16x16x32_bf16 v[0:3], v[152:155], v[204:207], v[0:3]
	v_mfma_f32_16x16x32_bf16 v[12:15], v[144:147], v[204:207], v[12:15]
	v_mfma_f32_16x16x32_bf16 v[60:63], v[148:151], v[184:187], v[60:63]
	v_mfma_f32_16x16x32_bf16 v[48:51], v[156:159], v[184:187], v[48:51]
	v_mfma_f32_16x16x32_bf16 v[56:59], v[164:167], v[184:187], v[56:59]
	v_mfma_f32_16x16x32_bf16 v[52:55], v[176:179], v[184:187], v[52:55]
	v_mfma_f32_16x16x32_bf16 v[36:39], v[176:179], v[192:195], v[36:39]
	v_mfma_f32_16x16x32_bf16 v[40:43], v[164:167], v[192:195], v[40:43]
	v_mfma_f32_16x16x32_bf16 v[32:35], v[156:159], v[192:195], v[32:35]
	v_mfma_f32_16x16x32_bf16 v[44:47], v[148:151], v[192:195], v[44:47]
	v_mfma_f32_16x16x32_bf16 v[28:31], v[148:151], v[200:203], v[28:31]
	v_mfma_f32_16x16x32_bf16 v[16:19], v[156:159], v[200:203], v[16:19]
	v_mfma_f32_16x16x32_bf16 v[24:27], v[164:167], v[200:203], v[24:27]
	v_mfma_f32_16x16x32_bf16 v[20:23], v[176:179], v[200:203], v[20:23]
	v_mfma_f32_16x16x32_bf16 v[4:7], v[176:179], v[212:215], v[4:7]
	v_mfma_f32_16x16x32_bf16 v[8:11], v[164:167], v[212:215], v[8:11]
	v_mfma_f32_16x16x32_bf16 v[0:3], v[156:159], v[212:215], v[0:3]
	v_mfma_f32_16x16x32_bf16 v[12:15], v[148:151], v[212:215], v[12:15]
	s_barrier
	s_cmp_gt_u32 s21, 13
	s_cbranch_scc0 .LBB0_970
	s_and_b64 vcc, exec, s[18:19]
	s_cbranch_vccz .LBB0_973
	s_barrier

.LBB0_1046:
	s_add_i32 s55, s55, 2
	s_mov_b32 s56, s55
	s_ashr_i32 s57, s56, 31
	s_lshl_b64 s[58:59], s[56:57], 7
	s_add_u32 s57, s58, 0x100
	s_addc_u32 s60, s59, 0
	s_add_u32 s61, s24, s57
	s_addc_u32 s62, s25, s60
	s_add_u32 s63, s22, s57
	s_addc_u32 s60, s23, s60
	s_cmp_eq_u32 s56, 42
	s_cselect_b32 s57, s1, s62
	s_cselect_b32 s56, s0, s61
	s_cselect_b32 s61, s27, s60
	s_cselect_b32 s60, s26, s63
	v_lshl_add_u64 v[208:209], v[136:137], 0, s[58:59]
	v_lshl_add_u64 v[216:217], v[208:209], 0, s[12:13]
	s_add_i32 m0, s39, 0xc000
	s_nop 0
	global_load_lds_dwordx4 v[216:217], off
	v_lshl_add_u64 v[208:209], v[208:209], 0, s[14:15]
	s_add_i32 m0, s39, 0xe000
	s_nop 0
	global_load_lds_dwordx4 v[208:209], off
	ds_read_b128 v[144:147], v140
	ds_read_b128 v[148:151], v140 offset:1024
	ds_read_b128 v[152:155], v140 offset:2048
	ds_read_b128 v[156:159], v140 offset:3072
	ds_read_b128 v[160:163], v141
	ds_read_b128 v[164:167], v141 offset:1024
	ds_read_b128 v[172:175], v141 offset:2048
	ds_read_b128 v[176:179], v141 offset:3072
	ds_read_b128 v[180:183], v142
	ds_read_b128 v[184:187], v142 offset:1024
	ds_read_b128 v[188:191], v142 offset:2048
	ds_read_b128 v[192:195], v142 offset:3072
	ds_read_b128 v[196:199], v142 offset:4096
	ds_read_b128 v[200:203], v142 offset:5120
	ds_read_b128 v[204:207], v142 offset:6144
	ds_read_b128 v[212:215], v142 offset:7168
	s_waitcnt vmcnt(8)
	s_waitcnt lgkmcnt(0)
	s_barrier
	s_waitcnt lgkmcnt(0)
	v_mfma_f32_16x16x32_bf16 v[124:127], v[144:147], v[180:183], v[124:127]
	v_mfma_f32_16x16x32_bf16 v[120:123], v[152:155], v[180:183], v[120:123]
	v_mfma_f32_16x16x32_bf16 v[108:111], v[160:163], v[180:183], v[108:111]
	v_mfma_f32_16x16x32_bf16 v[104:107], v[172:175], v[180:183], v[104:107]
	v_mfma_f32_16x16x32_bf16 v[88:91], v[172:175], v[188:191], v[88:91]
	v_mfma_f32_16x16x32_bf16 v[92:95], v[160:163], v[188:191], v[92:95]
	v_mfma_f32_16x16x32_bf16 v[112:115], v[152:155], v[188:191], v[112:115]
	v_mfma_f32_16x16x32_bf16 v[116:119], v[144:147], v[188:191], v[116:119]
	v_mfma_f32_16x16x32_bf16 v[100:103], v[144:147], v[196:199], v[100:103]
	v_mfma_f32_16x16x32_bf16 v[96:99], v[152:155], v[196:199], v[96:99]
	v_mfma_f32_16x16x32_bf16 v[76:79], v[160:163], v[196:199], v[76:79]
	v_mfma_f32_16x16x32_bf16 v[72:75], v[172:175], v[196:199], v[72:75]
	v_mfma_f32_16x16x32_bf16 v[64:67], v[172:175], v[204:207], v[64:67]
	v_mfma_f32_16x16x32_bf16 v[68:71], v[160:163], v[204:207], v[68:71]
	v_mfma_f32_16x16x32_bf16 v[80:83], v[152:155], v[204:207], v[80:83]
	v_mfma_f32_16x16x32_bf16 v[84:87], v[144:147], v[204:207], v[84:87]
	v_mfma_f32_16x16x32_bf16 v[124:127], v[148:151], v[184:187], v[124:127]
	v_mfma_f32_16x16x32_bf16 v[120:123], v[156:159], v[184:187], v[120:123]
	v_mfma_f32_16x16x32_bf16 v[108:111], v[164:167], v[184:187], v[108:111]
	v_mfma_f32_16x16x32_bf16 v[104:107], v[176:179], v[184:187], v[104:107]
	v_mfma_f32_16x16x32_bf16 v[88:91], v[176:179], v[192:195], v[88:91]
	v_mfma_f32_16x16x32_bf16 v[92:95], v[164:167], v[192:195], v[92:95]
	v_mfma_f32_16x16x32_bf16 v[112:115], v[156:159], v[192:195], v[112:115]
	v_mfma_f32_16x16x32_bf16 v[116:119], v[148:151], v[192:195], v[116:119]
	v_mfma_f32_16x16x32_bf16 v[100:103], v[148:151], v[200:203], v[100:103]
	v_mfma_f32_16x16x32_bf16 v[96:99], v[156:159], v[200:203], v[96:99]
	v_mfma_f32_16x16x32_bf16 v[76:79], v[164:167], v[200:203], v[76:79]
	v_mfma_f32_16x16x32_bf16 v[72:75], v[176:179], v[200:203], v[72:75]
	v_mfma_f32_16x16x32_bf16 v[64:67], v[176:179], v[212:215], v[64:67]
	v_mfma_f32_16x16x32_bf16 v[68:71], v[164:167], v[212:215], v[68:71]
	v_mfma_f32_16x16x32_bf16 v[80:83], v[156:159], v[212:215], v[80:83]
	v_mfma_f32_16x16x32_bf16 v[84:87], v[148:151], v[212:215], v[84:87]
	s_barrier
	s_add_i32 s58, s49, s38
	v_lshl_add_u64 v[208:209], s[60:61], 0, v[130:131]
	s_mov_b32 m0, s58
	s_nop 0
	global_load_lds_dwordx4 v[208:209], off
	v_lshl_add_u64 v[216:217], v[208:209], 0, s[2:3]
	s_add_i32 m0, s58, 0x2000
	s_add_i32 s58, s50, s38
	global_load_lds_dwordx4 v[216:217], off
	v_lshl_add_u64 v[216:217], v[208:209], 0, s[4:5]
	s_mov_b32 m0, s58
	s_nop 0
	global_load_lds_dwordx4 v[216:217], off
	v_lshl_add_u64 v[216:217], v[208:209], 0, s[6:7]
	s_add_i32 m0, s58, 0x2000
	s_nop 0
	global_load_lds_dwordx4 v[216:217], off
	v_lshl_add_u64 v[216:217], s[56:57], 0, v[128:129]
	s_mov_b32 m0, s39
	v_lshl_add_u64 v[218:219], v[216:217], 0, s[2:3]
	global_load_lds_dwordx4 v[216:217], off
	s_mov_b32 m0, s40
	s_nop 0
	global_load_lds_dwordx4 v[218:219], off
	ds_read_b128 v[180:183], v142 offset:16384
	ds_read_b128 v[184:187], v142 offset:17408
	ds_read_b128 v[188:191], v142 offset:18432
	ds_read_b128 v[192:195], v142 offset:19456
	ds_read_b128 v[196:199], v142 offset:20480
	ds_read_b128 v[200:203], v142 offset:21504
	ds_read_b128 v[204:207], v142 offset:22528
	ds_read_b128 v[212:215], v142 offset:23552
	s_waitcnt vmcnt(8)
	s_waitcnt lgkmcnt(0)
	s_barrier
	s_waitcnt lgkmcnt(0)
	v_mfma_f32_16x16x32_bf16 v[60:63], v[144:147], v[180:183], v[60:63]
	v_mfma_f32_16x16x32_bf16 v[56:59], v[152:155], v[180:183], v[56:59]
	v_mfma_f32_16x16x32_bf16 v[44:47], v[160:163], v[180:183], v[44:47]
	v_mfma_f32_16x16x32_bf16 v[40:43], v[172:175], v[180:183], v[40:43]
	v_mfma_f32_16x16x32_bf16 v[24:27], v[172:175], v[188:191], v[24:27]
	v_mfma_f32_16x16x32_bf16 v[28:31], v[160:163], v[188:191], v[28:31]
	v_mfma_f32_16x16x32_bf16 v[48:51], v[152:155], v[188:191], v[48:51]
	v_mfma_f32_16x16x32_bf16 v[52:55], v[144:147], v[188:191], v[52:55]
	v_mfma_f32_16x16x32_bf16 v[36:39], v[144:147], v[196:199], v[36:39]
	v_mfma_f32_16x16x32_bf16 v[32:35], v[152:155], v[196:199], v[32:35]
	v_mfma_f32_16x16x32_bf16 v[12:15], v[160:163], v[196:199], v[12:15]
	v_mfma_f32_16x16x32_bf16 v[8:11], v[172:175], v[196:199], v[8:11]
	v_mfma_f32_16x16x32_bf16 v[0:3], v[172:175], v[204:207], v[0:3]
	v_mfma_f32_16x16x32_bf16 v[4:7], v[160:163], v[204:207], v[4:7]
	v_mfma_f32_16x16x32_bf16 v[16:19], v[152:155], v[204:207], v[16:19]
	v_mfma_f32_16x16x32_bf16 v[20:23], v[144:147], v[204:207], v[20:23]
	v_mfma_f32_16x16x32_bf16 v[60:63], v[148:151], v[184:187], v[60:63]
	v_mfma_f32_16x16x32_bf16 v[56:59], v[156:159], v[184:187], v[56:59]
	v_mfma_f32_16x16x32_bf16 v[44:47], v[164:167], v[184:187], v[44:47]
	v_mfma_f32_16x16x32_bf16 v[40:43], v[176:179], v[184:187], v[40:43]
	v_mfma_f32_16x16x32_bf16 v[24:27], v[176:179], v[192:195], v[24:27]
	v_mfma_f32_16x16x32_bf16 v[28:31], v[164:167], v[192:195], v[28:31]
	v_mfma_f32_16x16x32_bf16 v[48:51], v[156:159], v[192:195], v[48:51]
	v_mfma_f32_16x16x32_bf16 v[52:55], v[148:151], v[192:195], v[52:55]
	v_mfma_f32_16x16x32_bf16 v[36:39], v[148:151], v[200:203], v[36:39]
	v_mfma_f32_16x16x32_bf16 v[32:35], v[156:159], v[200:203], v[32:35]
	v_mfma_f32_16x16x32_bf16 v[12:15], v[164:167], v[200:203], v[12:15]
	v_mfma_f32_16x16x32_bf16 v[8:11], v[176:179], v[200:203], v[8:11]
	v_mfma_f32_16x16x32_bf16 v[0:3], v[176:179], v[212:215], v[0:3]
	v_mfma_f32_16x16x32_bf16 v[4:7], v[164:167], v[212:215], v[4:7]
	v_mfma_f32_16x16x32_bf16 v[16:19], v[156:159], v[212:215], v[16:19]
	v_mfma_f32_16x16x32_bf16 v[20:23], v[148:151], v[212:215], v[20:23]
	s_barrier
	s_mov_b32 m0, s41
	v_lshl_add_u64 v[218:219], v[216:217], 0, s[4:5]
	global_load_lds_dwordx4 v[218:219], off
	v_lshl_add_u64 v[218:219], v[216:217], 0, s[6:7]
	s_mov_b32 m0, s42
	s_nop 0
	global_load_lds_dwordx4 v[218:219], off
	s_add_i32 s56, 0, 0x18000
	v_add_u32_e32 v143, s56, v139
	s_add_i32 s57, 0, 0x1c000
	ds_read_b128 v[144:147], v143
	ds_read_b128 v[148:151], v143 offset:1024
	ds_read_b128 v[152:155], v143 offset:2048
	ds_read_b128 v[156:159], v143 offset:3072
	v_add_u32_e32 v143, s57, v139
	ds_read_b128 v[160:163], v143
	ds_read_b128 v[164:167], v143 offset:1024
	ds_read_b128 v[172:175], v143 offset:2048
	ds_read_b128 v[176:179], v143 offset:3072
	ds_read_b128 v[180:183], v142 offset:32768
	ds_read_b128 v[184:187], v142 offset:33792
	ds_read_b128 v[188:191], v142 offset:34816
	ds_read_b128 v[192:195], v142 offset:35840
	ds_read_b128 v[196:199], v142 offset:36864
	ds_read_b128 v[200:203], v142 offset:37888
	ds_read_b128 v[204:207], v142 offset:38912
	ds_read_b128 v[212:215], v142 offset:39936
	s_nop 0
	s_waitcnt vmcnt(8)
	s_waitcnt lgkmcnt(0)
	s_barrier
	s_waitcnt lgkmcnt(0)
	v_mfma_f32_16x16x32_bf16 v[124:127], v[144:147], v[180:183], v[124:127]
	v_mfma_f32_16x16x32_bf16 v[120:123], v[152:155], v[180:183], v[120:123]
	v_mfma_f32_16x16x32_bf16 v[108:111], v[160:163], v[180:183], v[108:111]
	v_mfma_f32_16x16x32_bf16 v[104:107], v[172:175], v[180:183], v[104:107]
	v_mfma_f32_16x16x32_bf16 v[88:91], v[172:175], v[188:191], v[88:91]
	v_mfma_f32_16x16x32_bf16 v[92:95], v[160:163], v[188:191], v[92:95]
	v_mfma_f32_16x16x32_bf16 v[112:115], v[152:155], v[188:191], v[112:115]
	v_mfma_f32_16x16x32_bf16 v[116:119], v[144:147], v[188:191], v[116:119]
	v_mfma_f32_16x16x32_bf16 v[100:103], v[144:147], v[196:199], v[100:103]
	v_mfma_f32_16x16x32_bf16 v[96:99], v[152:155], v[196:199], v[96:99]
	v_mfma_f32_16x16x32_bf16 v[76:79], v[160:163], v[196:199], v[76:79]
	v_mfma_f32_16x16x32_bf16 v[72:75], v[172:175], v[196:199], v[72:75]
	v_mfma_f32_16x16x32_bf16 v[64:67], v[172:175], v[204:207], v[64:67]
	v_mfma_f32_16x16x32_bf16 v[68:71], v[160:163], v[204:207], v[68:71]
	v_mfma_f32_16x16x32_bf16 v[80:83], v[152:155], v[204:207], v[80:83]
	v_mfma_f32_16x16x32_bf16 v[84:87], v[144:147], v[204:207], v[84:87]
	v_mfma_f32_16x16x32_bf16 v[124:127], v[148:151], v[184:187], v[124:127]
	v_mfma_f32_16x16x32_bf16 v[120:123], v[156:159], v[184:187], v[120:123]
	v_mfma_f32_16x16x32_bf16 v[108:111], v[164:167], v[184:187], v[108:111]
	v_mfma_f32_16x16x32_bf16 v[104:107], v[176:179], v[184:187], v[104:107]
	v_mfma_f32_16x16x32_bf16 v[88:91], v[176:179], v[192:195], v[88:91]
	v_mfma_f32_16x16x32_bf16 v[92:95], v[164:167], v[192:195], v[92:95]
	v_mfma_f32_16x16x32_bf16 v[112:115], v[156:159], v[192:195], v[112:115]
	v_mfma_f32_16x16x32_bf16 v[116:119], v[148:151], v[192:195], v[116:119]
	v_mfma_f32_16x16x32_bf16 v[100:103], v[148:151], v[200:203], v[100:103]
	v_mfma_f32_16x16x32_bf16 v[96:99], v[156:159], v[200:203], v[96:99]
	v_mfma_f32_16x16x32_bf16 v[76:79], v[164:167], v[200:203], v[76:79]
	v_mfma_f32_16x16x32_bf16 v[72:75], v[176:179], v[200:203], v[72:75]
	v_mfma_f32_16x16x32_bf16 v[64:67], v[176:179], v[212:215], v[64:67]
	v_mfma_f32_16x16x32_bf16 v[68:71], v[164:167], v[212:215], v[68:71]
	v_mfma_f32_16x16x32_bf16 v[80:83], v[156:159], v[212:215], v[80:83]
	v_mfma_f32_16x16x32_bf16 v[84:87], v[148:151], v[212:215], v[84:87]
	s_barrier
	s_add_i32 s56, s56, s38
	v_lshl_add_u64 v[218:219], v[208:209], 0, s[12:13]
	s_mov_b32 m0, s56
	s_nop 0
	global_load_lds_dwordx4 v[218:219], off
	v_lshl_add_u64 v[218:219], v[208:209], 0, s[14:15]
	s_add_i32 m0, s56, 0x2000
	s_add_i32 s56, s57, s38
	global_load_lds_dwordx4 v[218:219], off
	v_lshl_add_u64 v[218:219], v[208:209], 0, s[16:17]
	s_mov_b32 m0, s56
	v_lshl_add_u64 v[208:209], v[208:209], 0, s[18:19]
	global_load_lds_dwordx4 v[218:219], off
	s_add_i32 m0, s56, 0x2000
	s_nop 0
	global_load_lds_dwordx4 v[208:209], off
	v_lshl_add_u64 v[208:209], v[216:217], 0, s[12:13]
	s_mov_b32 m0, s44
	s_nop 0
	global_load_lds_dwordx4 v[208:209], off
	v_lshl_add_u64 v[208:209], v[216:217], 0, s[14:15]
	s_mov_b32 m0, s45
	s_nop 0
	global_load_lds_dwordx4 v[208:209], off
	ds_read_b128 v[180:183], v142 offset:49152
	ds_read_b128 v[184:187], v142 offset:50176
	ds_read_b128 v[188:191], v142 offset:51200
	ds_read_b128 v[192:195], v142 offset:52224
	ds_read_b128 v[196:199], v142 offset:53248
	ds_read_b128 v[200:203], v142 offset:54272
	ds_read_b128 v[204:207], v142 offset:55296
	ds_read_b128 v[212:215], v142 offset:56320
	s_waitcnt vmcnt(8)
	s_waitcnt lgkmcnt(0)
	s_barrier
	s_waitcnt lgkmcnt(0)
	v_mfma_f32_16x16x32_bf16 v[60:63], v[144:147], v[180:183], v[60:63]
	v_mfma_f32_16x16x32_bf16 v[56:59], v[152:155], v[180:183], v[56:59]
	v_mfma_f32_16x16x32_bf16 v[44:47], v[160:163], v[180:183], v[44:47]
	v_mfma_f32_16x16x32_bf16 v[40:43], v[172:175], v[180:183], v[40:43]
	v_mfma_f32_16x16x32_bf16 v[24:27], v[172:175], v[188:191], v[24:27]
	v_mfma_f32_16x16x32_bf16 v[28:31], v[160:163], v[188:191], v[28:31]
	v_mfma_f32_16x16x32_bf16 v[48:51], v[152:155], v[188:191], v[48:51]
	v_mfma_f32_16x16x32_bf16 v[52:55], v[144:147], v[188:191], v[52:55]
	v_mfma_f32_16x16x32_bf16 v[36:39], v[144:147], v[196:199], v[36:39]
	v_mfma_f32_16x16x32_bf16 v[32:35], v[152:155], v[196:199], v[32:35]
	v_mfma_f32_16x16x32_bf16 v[12:15], v[160:163], v[196:199], v[12:15]
	v_mfma_f32_16x16x32_bf16 v[8:11], v[172:175], v[196:199], v[8:11]
	v_mfma_f32_16x16x32_bf16 v[0:3], v[172:175], v[204:207], v[0:3]
	v_mfma_f32_16x16x32_bf16 v[4:7], v[160:163], v[204:207], v[4:7]
	v_mfma_f32_16x16x32_bf16 v[16:19], v[152:155], v[204:207], v[16:19]
	v_mfma_f32_16x16x32_bf16 v[20:23], v[144:147], v[204:207], v[20:23]
	v_mfma_f32_16x16x32_bf16 v[60:63], v[148:151], v[184:187], v[60:63]
	v_mfma_f32_16x16x32_bf16 v[56:59], v[156:159], v[184:187], v[56:59]
	v_mfma_f32_16x16x32_bf16 v[44:47], v[164:167], v[184:187], v[44:47]
	v_mfma_f32_16x16x32_bf16 v[40:43], v[176:179], v[184:187], v[40:43]
	v_mfma_f32_16x16x32_bf16 v[24:27], v[176:179], v[192:195], v[24:27]
	v_mfma_f32_16x16x32_bf16 v[28:31], v[164:167], v[192:195], v[28:31]
	v_mfma_f32_16x16x32_bf16 v[48:51], v[156:159], v[192:195], v[48:51]
	v_mfma_f32_16x16x32_bf16 v[52:55], v[148:151], v[192:195], v[52:55]
	v_mfma_f32_16x16x32_bf16 v[36:39], v[148:151], v[200:203], v[36:39]
	v_mfma_f32_16x16x32_bf16 v[32:35], v[156:159], v[200:203], v[32:35]
	v_mfma_f32_16x16x32_bf16 v[12:15], v[164:167], v[200:203], v[12:15]
	v_mfma_f32_16x16x32_bf16 v[8:11], v[176:179], v[200:203], v[8:11]
	v_mfma_f32_16x16x32_bf16 v[0:3], v[176:179], v[212:215], v[0:3]
	v_mfma_f32_16x16x32_bf16 v[4:7], v[164:167], v[212:215], v[4:7]
	v_mfma_f32_16x16x32_bf16 v[16:19], v[156:159], v[212:215], v[16:19]
	v_mfma_f32_16x16x32_bf16 v[20:23], v[148:151], v[212:215], v[20:23]
	s_barrier
	s_cmp_gt_u32 s55, 41
	s_cbranch_scc0 .LBB0_1046
	s_and_b64 vcc, exec, s[20:21]
	s_cbranch_vccz .LBB0_1049
	s_barrier
